# candI with the per-MMA-block s_setprio 1/0 toggles removed from all GEMM main loops (uniform priority)
# speedup vs baseline: 1.0093x; 1.0093x over previous
; #define PG8_STAGE(bufoff, gbase, voff) do { _Pragma("unroll") for (int _i = 0; _i < 2; ++_i) \
;         __builtin_amdgcn_global_load_lds((const unsigned*)((const char*)(gbase) + (voff)[_i]), (PG8_LAS unsigned*)(lds + (bufoff) + ldsw + _i * 8192), 16, 0, 0); } while (0)
; #define PG8_LDA(dst, b, h) do { _Pragma("unroll") for (int m = 0; m < 4; ++m) _Pragma("unroll") for (int k = 0; k < 2; ++k) dst[m][k] = *(const PG8_LAS bf16x8*)(lds + PG8_SA(b, h) + aoff + m * 2048 + k * 1024); } while (0)
; #define PG8_LDB(dst, b, h) do { _Pragma("unroll") for (int n = 0; n < 2; ++n) _Pragma("unroll") for (int k = 0; k < 2; ++k) dst[n][k] = *(const PG8_LAS bf16x8*)(lds + PG8_SB(b, h) + boff + n * 2048 + k * 1024); } while (0)
; #define PG8_MMA(ai, bj, At, Bt) do { __builtin_amdgcn_s_setprio(1); _Pragma("unroll") for (int m = 0; m < 4; ++m) _Pragma("unroll") for (int n = 0; n < 2; ++n) _Pragma("unroll") for (int k = 0; k < 2; ++k) \
;         acc[ai][bj][m][n] = __builtin_amdgcn_mfma_f32_16x16x32_bf16(Bt[n][k], At[m][k], acc[ai][bj][m][n], 0, 0, 0); __builtin_amdgcn_s_setprio(0); } while (0)
; #define PG8_WAIT_V(n) asm volatile("s_waitcnt vmcnt(" #n ")" ::: "memory")
; #define PG8_WAIT_L(n) asm volatile("s_waitcnt lgkmcnt(" #n ")" ::: "memory")
; #define PG8_BAR __builtin_amdgcn_s_barrier()
; #define PG8_SCHED __builtin_amdgcn_sched_barrier(0)
; template <class Epi, class Sched, bool ALIGN_EPI = false, bool SP2 = false>
; __device__ __forceinline__ void gemm_phase(PG8_LAS unsigned char* lds, const Gemm g, const Sched& S, const Epi& E) {
;     ...
;             PG8_LDB(B0, 0, 0); PG8_LDB(B1, 0, 1); PG8_SCHED; PG8_LDA(At, 0, 0); PG8_STAGE(PG8_SA(1, 1), a1 + hstep, voffA);
;             PG8_WAIT_V(8); PG8_WAIT_L(0); PG8_BAR; PG8_MMA(0, 0, At, B0); PG8_MMA(0, 1, At, B1); PG8_BAR; PG8_SCHED;
;             PG8_LDA(At, 0, 1); PG8_STAGE(PG8_SB(0, 0), b2, voffB); PG8_STAGE(PG8_SB(0, 1), b2 + hstep, voffB); PG8_STAGE(PG8_SA(0, 0), a2, voffA);
;             PG8_WAIT_V(8); PG8_WAIT_L(0); PG8_BAR; PG8_MMA(1, 0, At, B0); PG8_MMA(1, 1, At, B1); PG8_BAR; PG8_SCHED;
.LBB0_130:
	ds_read_b128 v[34:37], v185
	ds_read_b128 v[38:41], v185 offset:1024
	ds_read_b128 v[42:45], v185 offset:2048
	ds_read_b128 v[46:49], v185 offset:3072
	ds_read_b128 v[146:149], v186
	ds_read_b128 v[150:153], v186 offset:1024
	ds_read_b128 v[174:177], v186 offset:2048
	ds_read_b128 v[192:195], v186 offset:3072
	s_add_u32 s0, s10, 0xfffc0080
	s_addc_u32 s1, s11, -1
	s_cmp_eq_u32 s51, 12
	s_cselect_b32 s13, s2, s1
	s_cselect_b32 s12, s7, s0
	s_cselect_b32 s1, s9, s50
	s_cselect_b32 s0, s28, s29
	v_lshl_add_u64 v[178:179], s[10:11], 0, v[166:167]
	s_add_i32 m0, s48, 0xc000
	ds_read_b128 v[196:199], v187
	ds_read_b128 v[200:203], v187 offset:1024
	ds_read_b128 v[204:207], v187 offset:2048
	ds_read_b128 v[208:211], v187 offset:3072
	ds_read_b128 v[212:215], v187 offset:4096
	ds_read_b128 v[216:219], v187 offset:5120
	ds_read_b128 v[220:223], v187 offset:6144
	ds_read_b128 v[224:227], v187 offset:7168
	global_load_lds_dwordx4 v[178:179], off
	v_lshl_add_u64 v[178:179], s[10:11], 0, v[168:169]
	s_add_i32 m0, s48, 0xe000
	s_nop 0
	global_load_lds_dwordx4 v[178:179], off
	s_waitcnt vmcnt(8)
	s_waitcnt lgkmcnt(0)
	s_barrier
	s_waitcnt lgkmcnt(0)
	v_mfma_f32_16x16x32_bf16 v[142:145], v[34:37], v[196:199], v[142:145]
	v_mfma_f32_16x16x32_bf16 v[138:141], v[42:45], v[196:199], v[138:141]
	v_mfma_f32_16x16x32_bf16 v[126:129], v[34:37], v[204:207], v[126:129]
	v_mfma_f32_16x16x32_bf16 v[122:125], v[42:45], v[204:207], v[122:125]
	v_mfma_f32_16x16x32_bf16 v[110:113], v[34:37], v[212:215], v[110:113]
	v_mfma_f32_16x16x32_bf16 v[106:109], v[42:45], v[212:215], v[106:109]
	v_mfma_f32_16x16x32_bf16 v[94:97], v[34:37], v[220:223], v[94:97]
	v_mfma_f32_16x16x32_bf16 v[90:93], v[42:45], v[220:223], v[90:93]
	v_mfma_f32_16x16x32_bf16 v[142:145], v[38:41], v[200:203], v[142:145]
	v_mfma_f32_16x16x32_bf16 v[138:141], v[46:49], v[200:203], v[138:141]
	v_mfma_f32_16x16x32_bf16 v[126:129], v[38:41], v[208:211], v[126:129]
	v_mfma_f32_16x16x32_bf16 v[122:125], v[46:49], v[208:211], v[122:125]
	v_mfma_f32_16x16x32_bf16 v[110:113], v[38:41], v[216:219], v[110:113]
	v_mfma_f32_16x16x32_bf16 v[106:109], v[46:49], v[216:219], v[106:109]
	v_mfma_f32_16x16x32_bf16 v[94:97], v[38:41], v[224:227], v[94:97]
	v_mfma_f32_16x16x32_bf16 v[90:93], v[46:49], v[224:227], v[90:93]
	v_mfma_f32_16x16x32_bf16 v[134:137], v[146:149], v[196:199], v[134:137]
	v_mfma_f32_16x16x32_bf16 v[130:133], v[174:177], v[196:199], v[130:133]
	v_mfma_f32_16x16x32_bf16 v[118:121], v[146:149], v[204:207], v[118:121]
	v_mfma_f32_16x16x32_bf16 v[114:117], v[174:177], v[204:207], v[114:117]
	v_mfma_f32_16x16x32_bf16 v[102:105], v[146:149], v[212:215], v[102:105]
	v_mfma_f32_16x16x32_bf16 v[98:101], v[174:177], v[212:215], v[98:101]
	v_mfma_f32_16x16x32_bf16 v[86:89], v[146:149], v[220:223], v[86:89]
	v_mfma_f32_16x16x32_bf16 v[82:85], v[174:177], v[220:223], v[82:85]
	v_mfma_f32_16x16x32_bf16 v[134:137], v[150:153], v[200:203], v[134:137]
	v_mfma_f32_16x16x32_bf16 v[130:133], v[192:195], v[200:203], v[130:133]
	v_mfma_f32_16x16x32_bf16 v[118:121], v[150:153], v[208:211], v[118:121]
	v_mfma_f32_16x16x32_bf16 v[114:117], v[192:195], v[208:211], v[114:117]
	v_mfma_f32_16x16x32_bf16 v[102:105], v[150:153], v[216:219], v[102:105]
	v_mfma_f32_16x16x32_bf16 v[98:101], v[192:195], v[216:219], v[98:101]
	v_mfma_f32_16x16x32_bf16 v[86:89], v[150:153], v[224:227], v[86:89]
	v_mfma_f32_16x16x32_bf16 v[82:85], v[192:195], v[224:227], v[82:85]
	s_barrier
	s_add_i32 s70, s21, s15
	v_lshl_add_u64 v[178:179], s[0:1], 0, v[158:159]
	s_mov_b32 m0, s70
	ds_read_b128 v[196:199], v187 offset:16384
	ds_read_b128 v[200:203], v187 offset:17408
	ds_read_b128 v[204:207], v187 offset:18432
	ds_read_b128 v[208:211], v187 offset:19456
	ds_read_b128 v[212:215], v187 offset:20480
	ds_read_b128 v[216:219], v187 offset:21504
	ds_read_b128 v[220:223], v187 offset:22528
	ds_read_b128 v[224:227], v187 offset:23552
	global_load_lds_dwordx4 v[178:179], off
	s_add_i32 m0, s70, 0x2000
	s_add_u32 s70, s0, 0x40000
	v_lshl_add_u64 v[228:229], s[0:1], 0, v[162:163]
	s_addc_u32 s71, s1, 0
	s_add_i32 s74, s20, s15
	global_load_lds_dwordx4 v[228:229], off
	v_lshl_add_u64 v[230:231], s[70:71], 0, v[158:159]
	s_mov_b32 m0, s74
	v_lshl_add_u64 v[232:233], s[12:13], 0, v[160:161]
	global_load_lds_dwordx4 v[230:231], off
	v_lshl_add_u64 v[230:231], s[70:71], 0, v[162:163]
	s_add_i32 m0, s74, 0x2000
	s_nop 0
	global_load_lds_dwordx4 v[230:231], off
	v_lshl_add_u64 v[230:231], s[12:13], 0, v[156:157]
	s_mov_b32 m0, s48
	s_nop 0
	global_load_lds_dwordx4 v[230:231], off
	s_mov_b32 m0, s49
	s_nop 0
	global_load_lds_dwordx4 v[232:233], off
	s_waitcnt vmcnt(8)
	s_waitcnt lgkmcnt(0)
	s_barrier
; #define PG8_STAGE(bufoff, gbase, voff) do { _Pragma("unroll") for (int _i = 0; _i < 2; ++_i) \
;         __builtin_amdgcn_global_load_lds((const unsigned*)((const char*)(gbase) + (voff)[_i]), (PG8_LAS unsigned*)(lds + (bufoff) + ldsw + _i * 8192), 16, 0, 0); } while (0)
; #define PG8_LDA(dst, b, h) do { _Pragma("unroll") for (int m = 0; m < 4; ++m) _Pragma("unroll") for (int k = 0; k < 2; ++k) dst[m][k] = *(const PG8_LAS bf16x8*)(lds + PG8_SA(b, h) + aoff + m * 2048 + k * 1024); } while (0)
; #define PG8_LDB(dst, b, h) do { _Pragma("unroll") for (int n = 0; n < 2; ++n) _Pragma("unroll") for (int k = 0; k < 2; ++k) dst[n][k] = *(const PG8_LAS bf16x8*)(lds + PG8_SB(b, h) + boff + n * 2048 + k * 1024); } while (0)
; #define PG8_MMA(ai, bj, At, Bt) do { __builtin_amdgcn_s_setprio(1); _Pragma("unroll") for (int m = 0; m < 4; ++m) _Pragma("unroll") for (int n = 0; n < 2; ++n) _Pragma("unroll") for (int k = 0; k < 2; ++k) \
;         acc[ai][bj][m][n] = __builtin_amdgcn_mfma_f32_16x16x32_bf16(Bt[n][k], At[m][k], acc[ai][bj][m][n], 0, 0, 0); __builtin_amdgcn_s_setprio(0); } while (0)
; #define PG8_WAIT_V(n) asm volatile("s_waitcnt vmcnt(" #n ")" ::: "memory")
; #define PG8_WAIT_L(n) asm volatile("s_waitcnt lgkmcnt(" #n ")" ::: "memory")
; #define PG8_BAR __builtin_amdgcn_s_barrier()
; #define PG8_SCHED __builtin_amdgcn_sched_barrier(0)
; template <class Epi, class Sched, bool ALIGN_EPI = false, bool SP2 = false>
; __device__ __forceinline__ void gemm_phase(PG8_LAS unsigned char* lds, const Gemm g, const Sched& S, const Epi& E) {
;     ...
;             PG8_WAIT_V(8); PG8_WAIT_L(0); PG8_BAR; PG8_MMA(1, 0, At, B0); PG8_MMA(1, 1, At, B1); PG8_BAR; PG8_SCHED;
;             PG8_LDB(B0, 1, 0); PG8_LDB(B1, 1, 1); PG8_SCHED; PG8_LDA(At, 1, 0); PG8_STAGE(PG8_SA(0, 1), a2 + hstep, voffA);
;             PG8_WAIT_V(8); PG8_WAIT_L(0); PG8_BAR; PG8_MMA(0, 0, At, B0); PG8_MMA(0, 1, At, B1); PG8_BAR; PG8_SCHED;
	s_waitcnt lgkmcnt(0)
	v_mfma_f32_16x16x32_bf16 v[78:81], v[34:37], v[196:199], v[78:81]
	v_mfma_f32_16x16x32_bf16 v[74:77], v[42:45], v[196:199], v[74:77]
	v_mfma_f32_16x16x32_bf16 v[62:65], v[34:37], v[204:207], v[62:65]
	v_mfma_f32_16x16x32_bf16 v[58:61], v[42:45], v[204:207], v[58:61]
	v_mfma_f32_16x16x32_bf16 v[30:33], v[34:37], v[212:215], v[30:33]
	v_mfma_f32_16x16x32_bf16 v[26:29], v[42:45], v[212:215], v[26:29]
	v_mfma_f32_16x16x32_bf16 v[14:17], v[34:37], v[220:223], v[14:17]
	v_mfma_f32_16x16x32_bf16 v[10:13], v[42:45], v[220:223], v[10:13]
	v_mfma_f32_16x16x32_bf16 v[78:81], v[38:41], v[200:203], v[78:81]
	v_mfma_f32_16x16x32_bf16 v[74:77], v[46:49], v[200:203], v[74:77]
	v_mfma_f32_16x16x32_bf16 v[62:65], v[38:41], v[208:211], v[62:65]
	v_mfma_f32_16x16x32_bf16 v[58:61], v[46:49], v[208:211], v[58:61]
	v_mfma_f32_16x16x32_bf16 v[30:33], v[38:41], v[216:219], v[30:33]
	v_mfma_f32_16x16x32_bf16 v[26:29], v[46:49], v[216:219], v[26:29]
	v_mfma_f32_16x16x32_bf16 v[14:17], v[38:41], v[224:227], v[14:17]
	v_mfma_f32_16x16x32_bf16 v[10:13], v[46:49], v[224:227], v[10:13]
	v_mfma_f32_16x16x32_bf16 v[22:25], v[146:149], v[212:215], v[22:25]
	v_mfma_f32_16x16x32_bf16 v[18:21], v[174:177], v[212:215], v[18:21]
	v_mfma_f32_16x16x32_bf16 v[6:9], v[146:149], v[220:223], v[6:9]
	v_mfma_f32_16x16x32_bf16 v[2:5], v[174:177], v[220:223], v[2:5]
	v_mfma_f32_16x16x32_bf16 v[34:37], v[146:149], v[196:199], v[70:73]
	v_mfma_f32_16x16x32_bf16 v[38:41], v[174:177], v[196:199], v[66:69]
	v_mfma_f32_16x16x32_bf16 v[42:45], v[146:149], v[204:207], v[54:57]
	v_mfma_f32_16x16x32_bf16 v[46:49], v[174:177], v[204:207], v[50:53]
	v_mfma_f32_16x16x32_bf16 v[22:25], v[150:153], v[216:219], v[22:25]
	v_mfma_f32_16x16x32_bf16 v[18:21], v[192:195], v[216:219], v[18:21]
	v_mfma_f32_16x16x32_bf16 v[6:9], v[150:153], v[224:227], v[6:9]
	v_mfma_f32_16x16x32_bf16 v[2:5], v[192:195], v[224:227], v[2:5]
	v_mfma_f32_16x16x32_bf16 v[34:37], v[150:153], v[200:203], v[34:37]
	v_mfma_f32_16x16x32_bf16 v[38:41], v[192:195], v[200:203], v[38:41]
	v_mfma_f32_16x16x32_bf16 v[42:45], v[150:153], v[208:211], v[42:45]
	v_mfma_f32_16x16x32_bf16 v[46:49], v[192:195], v[208:211], v[46:49]
	s_barrier
	s_add_i32 s70, 0, 0x18000
	s_add_i32 s71, 0, 0x1c000
	v_add_u32_e32 v70, s70, v155
	v_add_u32_e32 v164, s71, v155
	ds_read_b128 v[50:53], v70
	ds_read_b128 v[54:57], v70 offset:1024
	ds_read_b128 v[66:69], v70 offset:2048
	ds_read_b128 v[70:73], v70 offset:3072
	ds_read_b128 v[146:149], v164
	ds_read_b128 v[150:153], v164 offset:1024
	ds_read_b128 v[174:177], v164 offset:2048
	ds_read_b128 v[192:195], v164 offset:3072
	s_add_u32 s12, s12, 0x40000
	s_addc_u32 s13, s13, 0
	s_mov_b32 m0, s33
	v_lshl_add_u64 v[234:235], s[12:13], 0, v[156:157]
	ds_read_b128 v[196:199], v187 offset:32768
	ds_read_b128 v[200:203], v187 offset:33792
	ds_read_b128 v[204:207], v187 offset:34816
	ds_read_b128 v[208:211], v187 offset:35840
	ds_read_b128 v[212:215], v187 offset:36864
	ds_read_b128 v[216:219], v187 offset:37888
	ds_read_b128 v[220:223], v187 offset:38912
	ds_read_b128 v[224:227], v187 offset:39936
	global_load_lds_dwordx4 v[234:235], off
	v_lshl_add_u64 v[234:235], s[12:13], 0, v[160:161]
	s_mov_b32 m0, s78
	s_nop 0
	global_load_lds_dwordx4 v[234:235], off
	s_waitcnt vmcnt(8)
	s_waitcnt lgkmcnt(0)
	s_barrier
	s_waitcnt lgkmcnt(0)
	v_mfma_f32_16x16x32_bf16 v[142:145], v[50:53], v[196:199], v[142:145]
	v_mfma_f32_16x16x32_bf16 v[138:141], v[66:69], v[196:199], v[138:141]
	v_mfma_f32_16x16x32_bf16 v[126:129], v[50:53], v[204:207], v[126:129]
	v_mfma_f32_16x16x32_bf16 v[122:125], v[66:69], v[204:207], v[122:125]
	v_mfma_f32_16x16x32_bf16 v[110:113], v[50:53], v[212:215], v[110:113]
	v_mfma_f32_16x16x32_bf16 v[106:109], v[66:69], v[212:215], v[106:109]
	v_mfma_f32_16x16x32_bf16 v[94:97], v[50:53], v[220:223], v[94:97]
	v_mfma_f32_16x16x32_bf16 v[90:93], v[66:69], v[220:223], v[90:93]
	v_mfma_f32_16x16x32_bf16 v[142:145], v[54:57], v[200:203], v[142:145]
	v_mfma_f32_16x16x32_bf16 v[138:141], v[70:73], v[200:203], v[138:141]
	v_mfma_f32_16x16x32_bf16 v[126:129], v[54:57], v[208:211], v[126:129]
	v_mfma_f32_16x16x32_bf16 v[122:125], v[70:73], v[208:211], v[122:125]
	v_mfma_f32_16x16x32_bf16 v[110:113], v[54:57], v[216:219], v[110:113]
	v_mfma_f32_16x16x32_bf16 v[106:109], v[70:73], v[216:219], v[106:109]
	v_mfma_f32_16x16x32_bf16 v[94:97], v[54:57], v[224:227], v[94:97]
	v_mfma_f32_16x16x32_bf16 v[90:93], v[70:73], v[224:227], v[90:93]
	v_mfma_f32_16x16x32_bf16 v[134:137], v[146:149], v[196:199], v[134:137]
	v_mfma_f32_16x16x32_bf16 v[130:133], v[174:177], v[196:199], v[130:133]
	v_mfma_f32_16x16x32_bf16 v[118:121], v[146:149], v[204:207], v[118:121]
	v_mfma_f32_16x16x32_bf16 v[114:117], v[174:177], v[204:207], v[114:117]
	v_mfma_f32_16x16x32_bf16 v[102:105], v[146:149], v[212:215], v[102:105]
	v_mfma_f32_16x16x32_bf16 v[98:101], v[174:177], v[212:215], v[98:101]
	v_mfma_f32_16x16x32_bf16 v[86:89], v[146:149], v[220:223], v[86:89]
	v_mfma_f32_16x16x32_bf16 v[82:85], v[174:177], v[220:223], v[82:85]
	v_mfma_f32_16x16x32_bf16 v[134:137], v[150:153], v[200:203], v[134:137]
	v_mfma_f32_16x16x32_bf16 v[130:133], v[192:195], v[200:203], v[130:133]
	v_mfma_f32_16x16x32_bf16 v[118:121], v[150:153], v[208:211], v[118:121]
	v_mfma_f32_16x16x32_bf16 v[114:117], v[192:195], v[208:211], v[114:117]
	v_mfma_f32_16x16x32_bf16 v[102:105], v[150:153], v[216:219], v[102:105]
	v_mfma_f32_16x16x32_bf16 v[98:101], v[192:195], v[216:219], v[98:101]
	v_mfma_f32_16x16x32_bf16 v[86:89], v[150:153], v[224:227], v[86:89]
	v_mfma_f32_16x16x32_bf16 v[82:85], v[192:195], v[224:227], v[82:85]
	s_barrier
; #define PG8_STAGE(bufoff, gbase, voff) do { _Pragma("unroll") for (int _i = 0; _i < 2; ++_i) \
;         __builtin_amdgcn_global_load_lds((const unsigned*)((const char*)(gbase) + (voff)[_i]), (PG8_LAS unsigned*)(lds + (bufoff) + ldsw + _i * 8192), 16, 0, 0); } while (0)
; #define PG8_LDA(dst, b, h) do { _Pragma("unroll") for (int m = 0; m < 4; ++m) _Pragma("unroll") for (int k = 0; k < 2; ++k) dst[m][k] = *(const PG8_LAS bf16x8*)(lds + PG8_SA(b, h) + aoff + m * 2048 + k * 1024); } while (0)
; #define PG8_MMA(ai, bj, At, Bt) do { __builtin_amdgcn_s_setprio(1); _Pragma("unroll") for (int m = 0; m < 4; ++m) _Pragma("unroll") for (int n = 0; n < 2; ++n) _Pragma("unroll") for (int k = 0; k < 2; ++k) \
;         acc[ai][bj][m][n] = __builtin_amdgcn_mfma_f32_16x16x32_bf16(Bt[n][k], At[m][k], acc[ai][bj][m][n], 0, 0, 0); __builtin_amdgcn_s_setprio(0); } while (0)
; #define PG8_WAIT_V(n) asm volatile("s_waitcnt vmcnt(" #n ")" ::: "memory")
; #define PG8_WAIT_L(n) asm volatile("s_waitcnt lgkmcnt(" #n ")" ::: "memory")
; #define PG8_BAR __builtin_amdgcn_s_barrier()
; #define PG8_SCHED __builtin_amdgcn_sched_barrier(0)
; template <class Epi, class Sched, bool ALIGN_EPI = false, bool SP2 = false>
; __device__ __forceinline__ void gemm_phase(PG8_LAS unsigned char* lds, const Gemm g, const Sched& S, const Epi& E) {
;     ...
;         for (int t = 0; t < nt; t += 2) {
;             const bool last = (t == nt - 2);
;             const char* a1 = cA + (size_t)(t + 1) * kstep;
;             const char* a2 = last ? nA : cA + (size_t)(t + 2) * kstep; const char* b2 = last ? nB : cB + (size_t)(t + 2) * kstep;
;     ...
;             PG8_LDA(At, 1, 1); PG8_STAGE(PG8_SB(1, 0), b3, voffB); PG8_STAGE(PG8_SB(1, 1), b3 + hstep, voffB); PG8_STAGE(PG8_SA(1, 0), a3, voffA);
;             PG8_WAIT_V(8); PG8_WAIT_L(0); PG8_BAR; PG8_MMA(1, 0, At, B0); PG8_MMA(1, 1, At, B1); PG8_BAR; PG8_SCHED;
	s_add_i32 s12, s70, s15
	v_lshl_add_u64 v[178:179], v[178:179], 0, s[34:35]
	s_mov_b32 m0, s12
	ds_read_b128 v[196:199], v187 offset:49152
	ds_read_b128 v[200:203], v187 offset:50176
	ds_read_b128 v[204:207], v187 offset:51200
	ds_read_b128 v[208:211], v187 offset:52224
	ds_read_b128 v[212:215], v187 offset:53248
	ds_read_b128 v[216:219], v187 offset:54272
	ds_read_b128 v[220:223], v187 offset:55296
	ds_read_b128 v[224:227], v187 offset:56320
	global_load_lds_dwordx4 v[178:179], off
	s_add_i32 m0, s12, 0x2000
	s_add_u32 s0, s0, 0x40080
	v_lshl_add_u64 v[178:179], v[228:229], 0, s[34:35]
	s_addc_u32 s1, s1, 0
	s_add_i32 s12, s71, s15
	global_load_lds_dwordx4 v[178:179], off
	v_lshl_add_u64 v[178:179], s[0:1], 0, v[158:159]
	s_mov_b32 m0, s12
	s_nop 0
	global_load_lds_dwordx4 v[178:179], off
	v_lshl_add_u64 v[178:179], s[0:1], 0, v[162:163]
	s_add_i32 m0, s12, 0x2000
	s_nop 0
	global_load_lds_dwordx4 v[178:179], off
	v_lshl_add_u64 v[178:179], v[230:231], 0, s[34:35]
	s_mov_b32 m0, s22
	s_nop 0
	global_load_lds_dwordx4 v[178:179], off
	v_lshl_add_u64 v[178:179], v[232:233], 0, s[34:35]
	s_mov_b32 m0, s23
	s_nop 0
	global_load_lds_dwordx4 v[178:179], off
	s_waitcnt vmcnt(8)
	s_waitcnt lgkmcnt(0)
	s_barrier
	s_waitcnt lgkmcnt(0)
	v_mfma_f32_16x16x32_bf16 v[78:81], v[50:53], v[196:199], v[78:81]
	v_mfma_f32_16x16x32_bf16 v[74:77], v[66:69], v[196:199], v[74:77]
	v_mfma_f32_16x16x32_bf16 v[62:65], v[50:53], v[204:207], v[62:65]
	v_mfma_f32_16x16x32_bf16 v[58:61], v[66:69], v[204:207], v[58:61]
	v_mfma_f32_16x16x32_bf16 v[30:33], v[50:53], v[212:215], v[30:33]
	v_mfma_f32_16x16x32_bf16 v[26:29], v[66:69], v[212:215], v[26:29]
	v_mfma_f32_16x16x32_bf16 v[14:17], v[50:53], v[220:223], v[14:17]
	v_mfma_f32_16x16x32_bf16 v[10:13], v[66:69], v[220:223], v[10:13]
	v_mfma_f32_16x16x32_bf16 v[78:81], v[54:57], v[200:203], v[78:81]
	v_mfma_f32_16x16x32_bf16 v[74:77], v[70:73], v[200:203], v[74:77]
	v_mfma_f32_16x16x32_bf16 v[62:65], v[54:57], v[208:211], v[62:65]
	v_mfma_f32_16x16x32_bf16 v[58:61], v[70:73], v[208:211], v[58:61]
	v_mfma_f32_16x16x32_bf16 v[30:33], v[54:57], v[216:219], v[30:33]
	v_mfma_f32_16x16x32_bf16 v[26:29], v[70:73], v[216:219], v[26:29]
	v_mfma_f32_16x16x32_bf16 v[14:17], v[54:57], v[224:227], v[14:17]
	v_mfma_f32_16x16x32_bf16 v[10:13], v[70:73], v[224:227], v[10:13]
	v_mfma_f32_16x16x32_bf16 v[34:37], v[146:149], v[196:199], v[34:37]
	v_mfma_f32_16x16x32_bf16 v[70:73], v[150:153], v[200:203], v[34:37]
	v_mfma_f32_16x16x32_bf16 v[34:37], v[174:177], v[196:199], v[38:41]
	v_mfma_f32_16x16x32_bf16 v[66:69], v[192:195], v[200:203], v[34:37]
	v_mfma_f32_16x16x32_bf16 v[34:37], v[146:149], v[204:207], v[42:45]
	v_mfma_f32_16x16x32_bf16 v[54:57], v[150:153], v[208:211], v[34:37]
	v_mfma_f32_16x16x32_bf16 v[34:37], v[174:177], v[204:207], v[46:49]
	v_mfma_f32_16x16x32_bf16 v[22:25], v[146:149], v[212:215], v[22:25]
	v_mfma_f32_16x16x32_bf16 v[18:21], v[174:177], v[212:215], v[18:21]
	v_mfma_f32_16x16x32_bf16 v[6:9], v[146:149], v[220:223], v[6:9]
	v_mfma_f32_16x16x32_bf16 v[2:5], v[174:177], v[220:223], v[2:5]
	v_mfma_f32_16x16x32_bf16 v[50:53], v[192:195], v[208:211], v[34:37]
	v_mfma_f32_16x16x32_bf16 v[22:25], v[150:153], v[216:219], v[22:25]
	v_mfma_f32_16x16x32_bf16 v[18:21], v[192:195], v[216:219], v[18:21]
	v_mfma_f32_16x16x32_bf16 v[6:9], v[150:153], v[224:227], v[6:9]
	v_mfma_f32_16x16x32_bf16 v[2:5], v[192:195], v[224:227], v[2:5]
	s_barrier
	s_add_i32 s51, s51, 2
	s_add_u32 s10, s10, 0x100
	s_addc_u32 s11, s11, 0
	s_add_u32 s29, s29, 0x100
	s_addc_u32 s50, s50, 0
	s_cmp_gt_u32 s51, 13
	s_cbranch_scc0 .LBB0_130
	v_readlane_b32 s0, v240, 20
	v_readlane_b32 s1, v240, 21
	s_and_b64 vcc, exec, s[0:1]
	s_cbranch_vccz .LBB0_133
	s_barrier

; #define PG8_STAGE(bufoff, gbase, voff) do { _Pragma("unroll") for (int _i = 0; _i < 2; ++_i) \
;         __builtin_amdgcn_global_load_lds((const unsigned*)((const char*)(gbase) + (voff)[_i]), (PG8_LAS unsigned*)(lds + (bufoff) + ldsw + _i * 8192), 16, 0, 0); } while (0)
; #define PG8_LDA(dst, b, h) do { _Pragma("unroll") for (int m = 0; m < 4; ++m) _Pragma("unroll") for (int k = 0; k < 2; ++k) dst[m][k] = *(const PG8_LAS bf16x8*)(lds + PG8_SA(b, h) + aoff + m * 2048 + k * 1024); } while (0)
; #define PG8_LDB(dst, b, h) do { _Pragma("unroll") for (int n = 0; n < 2; ++n) _Pragma("unroll") for (int k = 0; k < 2; ++k) dst[n][k] = *(const PG8_LAS bf16x8*)(lds + PG8_SB(b, h) + boff + n * 2048 + k * 1024); } while (0)
; #define PG8_MMA(ai, bj, At, Bt) do { __builtin_amdgcn_s_setprio(1); _Pragma("unroll") for (int m = 0; m < 4; ++m) _Pragma("unroll") for (int n = 0; n < 2; ++n) _Pragma("unroll") for (int k = 0; k < 2; ++k) \
;         acc[ai][bj][m][n] = __builtin_amdgcn_mfma_f32_16x16x32_bf16(Bt[n][k], At[m][k], acc[ai][bj][m][n], 0, 0, 0); __builtin_amdgcn_s_setprio(0); } while (0)
; #define PG8_WAIT_V(n) asm volatile("s_waitcnt vmcnt(" #n ")" ::: "memory")
; #define PG8_WAIT_L(n) asm volatile("s_waitcnt lgkmcnt(" #n ")" ::: "memory")
; #define PG8_BAR __builtin_amdgcn_s_barrier()
; #define PG8_SCHED __builtin_amdgcn_sched_barrier(0)
; template <class Epi, class Sched, bool ALIGN_EPI = false, bool SP2 = false>
; __device__ __forceinline__ void gemm_phase(PG8_LAS unsigned char* lds, const Gemm g, const Sched& S, const Epi& E) {
;     ...
;             PG8_LDB(B0, 0, 0); PG8_LDB(B1, 0, 1); PG8_SCHED; PG8_LDA(At, 0, 0); PG8_STAGE(PG8_SA(1, 1), a1 + hstep, voffA);
;             PG8_WAIT_V(8); PG8_WAIT_L(0); PG8_BAR; PG8_MMA(0, 0, At, B0); PG8_MMA(0, 1, At, B1); PG8_BAR; PG8_SCHED;
;             PG8_LDA(At, 0, 1); PG8_STAGE(PG8_SB(0, 0), b2, voffB); PG8_STAGE(PG8_SB(0, 1), b2 + hstep, voffB); PG8_STAGE(PG8_SA(0, 0), a2, voffA);
;             PG8_WAIT_V(8); PG8_WAIT_L(0); PG8_BAR; PG8_MMA(1, 0, At, B0); PG8_MMA(1, 1, At, B1); PG8_BAR; PG8_SCHED;
.LBB0_775:
	v_add_u32_e32 v134, s74, v156
	ds_read_b128 v[144:147], v134
	ds_read_b128 v[160:163], v134 offset:1024
	ds_read_b128 v[164:167], v134 offset:2048
	ds_read_b128 v[168:171], v134 offset:3072
	v_add_u32_e32 v134, s75, v156
	ds_read_b128 v[172:175], v134
	ds_read_b128 v[176:179], v134 offset:1024
	ds_read_b128 v[180:183], v134 offset:2048
	ds_read_b128 v[184:187], v134 offset:3072
	s_add_u32 s62, s0, 0xfffc0080
	s_addc_u32 s63, s1, -1
	s_cmp_eq_u32 s81, 12
	s_cselect_b32 s65, s35, s63
	s_cselect_b32 s64, s77, s62
	s_cselect_b32 s63, s31, s80
	s_cselect_b32 s62, s78, s79
	v_lshl_add_u64 v[220:221], s[0:1], 0, v[136:137]
	s_add_i32 m0, s53, 0xc000
	ds_read_b128 v[188:191], v158
	ds_read_b128 v[192:195], v158 offset:1024
	ds_read_b128 v[196:199], v158 offset:2048
	ds_read_b128 v[200:203], v158 offset:3072
	ds_read_b128 v[204:207], v158 offset:4096
	ds_read_b128 v[208:211], v158 offset:5120
	ds_read_b128 v[212:215], v158 offset:6144
	ds_read_b128 v[216:219], v158 offset:7168
	global_load_lds_dwordx4 v[220:221], off
	v_lshl_add_u64 v[220:221], s[0:1], 0, v[138:139]
	s_add_i32 m0, s53, 0xe000
	s_nop 0
	global_load_lds_dwordx4 v[220:221], off
	s_waitcnt vmcnt(8)
	s_waitcnt lgkmcnt(0)
	s_barrier
	s_waitcnt lgkmcnt(0)
	v_mfma_f32_16x16x32_bf16 v[126:129], v[144:147], v[188:191], v[126:129]
	v_mfma_f32_16x16x32_bf16 v[122:125], v[164:167], v[188:191], v[122:125]
	v_mfma_f32_16x16x32_bf16 v[110:113], v[144:147], v[196:199], v[110:113]
	v_mfma_f32_16x16x32_bf16 v[106:109], v[164:167], v[196:199], v[106:109]
	v_mfma_f32_16x16x32_bf16 v[94:97], v[144:147], v[204:207], v[94:97]
	v_mfma_f32_16x16x32_bf16 v[90:93], v[164:167], v[204:207], v[90:93]
	v_mfma_f32_16x16x32_bf16 v[78:81], v[144:147], v[212:215], v[78:81]
	v_mfma_f32_16x16x32_bf16 v[74:77], v[164:167], v[212:215], v[74:77]
	v_mfma_f32_16x16x32_bf16 v[126:129], v[160:163], v[192:195], v[126:129]
	v_mfma_f32_16x16x32_bf16 v[122:125], v[168:171], v[192:195], v[122:125]
	v_mfma_f32_16x16x32_bf16 v[110:113], v[160:163], v[200:203], v[110:113]
	v_mfma_f32_16x16x32_bf16 v[106:109], v[168:171], v[200:203], v[106:109]
	v_mfma_f32_16x16x32_bf16 v[94:97], v[160:163], v[208:211], v[94:97]
	v_mfma_f32_16x16x32_bf16 v[90:93], v[168:171], v[208:211], v[90:93]
	v_mfma_f32_16x16x32_bf16 v[78:81], v[160:163], v[216:219], v[78:81]
	v_mfma_f32_16x16x32_bf16 v[74:77], v[168:171], v[216:219], v[74:77]
	v_mfma_f32_16x16x32_bf16 v[118:121], v[172:175], v[188:191], v[118:121]
	v_mfma_f32_16x16x32_bf16 v[114:117], v[180:183], v[188:191], v[114:117]
	v_mfma_f32_16x16x32_bf16 v[102:105], v[172:175], v[196:199], v[102:105]
	v_mfma_f32_16x16x32_bf16 v[98:101], v[180:183], v[196:199], v[98:101]
	v_mfma_f32_16x16x32_bf16 v[86:89], v[172:175], v[204:207], v[86:89]
	v_mfma_f32_16x16x32_bf16 v[82:85], v[180:183], v[204:207], v[82:85]
	v_mfma_f32_16x16x32_bf16 v[70:73], v[172:175], v[212:215], v[70:73]
	v_mfma_f32_16x16x32_bf16 v[62:65], v[180:183], v[212:215], v[62:65]
	v_mfma_f32_16x16x32_bf16 v[118:121], v[176:179], v[192:195], v[118:121]
	v_mfma_f32_16x16x32_bf16 v[114:117], v[184:187], v[192:195], v[114:117]
	v_mfma_f32_16x16x32_bf16 v[102:105], v[176:179], v[200:203], v[102:105]
	v_mfma_f32_16x16x32_bf16 v[98:101], v[184:187], v[200:203], v[98:101]
	v_mfma_f32_16x16x32_bf16 v[86:89], v[176:179], v[208:211], v[86:89]
	v_mfma_f32_16x16x32_bf16 v[82:85], v[184:187], v[208:211], v[82:85]
	v_mfma_f32_16x16x32_bf16 v[70:73], v[176:179], v[216:219], v[70:73]
	v_mfma_f32_16x16x32_bf16 v[62:65], v[184:187], v[216:219], v[62:65]
	s_barrier
	s_add_i32 s82, s74, s66
	v_lshl_add_u64 v[220:221], s[62:63], 0, v[130:131]
	s_mov_b32 m0, s82
	ds_read_b128 v[188:191], v158 offset:16384
	ds_read_b128 v[192:195], v158 offset:17408
	ds_read_b128 v[196:199], v158 offset:18432
	ds_read_b128 v[200:203], v158 offset:19456
	ds_read_b128 v[204:207], v158 offset:20480
	ds_read_b128 v[208:211], v158 offset:21504
	ds_read_b128 v[212:215], v158 offset:22528
	ds_read_b128 v[216:219], v158 offset:23552
	global_load_lds_dwordx4 v[220:221], off
	s_add_i32 m0, s82, 0x2000
	s_add_u32 s82, s62, 0x40000
	v_lshl_add_u64 v[222:223], s[62:63], 0, v[132:133]
	s_addc_u32 s83, s63, 0
	s_add_i32 s84, s75, s66
	global_load_lds_dwordx4 v[222:223], off
	v_lshl_add_u64 v[224:225], s[82:83], 0, v[130:131]
	s_mov_b32 m0, s84
	v_lshl_add_u64 v[226:227], s[64:65], 0, v[132:133]
	global_load_lds_dwordx4 v[224:225], off
	v_lshl_add_u64 v[224:225], s[82:83], 0, v[132:133]
	s_add_i32 m0, s84, 0x2000
	s_nop 0
	global_load_lds_dwordx4 v[224:225], off
	v_lshl_add_u64 v[224:225], s[64:65], 0, v[130:131]
	s_mov_b32 m0, s53
	s_nop 0
	global_load_lds_dwordx4 v[224:225], off
	s_mov_b32 m0, s57
	s_nop 0
	global_load_lds_dwordx4 v[226:227], off
	s_waitcnt vmcnt(8)
	s_waitcnt lgkmcnt(0)
	s_barrier
; #define PG8_STAGE(bufoff, gbase, voff) do { _Pragma("unroll") for (int _i = 0; _i < 2; ++_i) \
;         __builtin_amdgcn_global_load_lds((const unsigned*)((const char*)(gbase) + (voff)[_i]), (PG8_LAS unsigned*)(lds + (bufoff) + ldsw + _i * 8192), 16, 0, 0); } while (0)
; #define PG8_LDA(dst, b, h) do { _Pragma("unroll") for (int m = 0; m < 4; ++m) _Pragma("unroll") for (int k = 0; k < 2; ++k) dst[m][k] = *(const PG8_LAS bf16x8*)(lds + PG8_SA(b, h) + aoff + m * 2048 + k * 1024); } while (0)
; #define PG8_LDB(dst, b, h) do { _Pragma("unroll") for (int n = 0; n < 2; ++n) _Pragma("unroll") for (int k = 0; k < 2; ++k) dst[n][k] = *(const PG8_LAS bf16x8*)(lds + PG8_SB(b, h) + boff + n * 2048 + k * 1024); } while (0)
; #define PG8_MMA(ai, bj, At, Bt) do { __builtin_amdgcn_s_setprio(1); _Pragma("unroll") for (int m = 0; m < 4; ++m) _Pragma("unroll") for (int n = 0; n < 2; ++n) _Pragma("unroll") for (int k = 0; k < 2; ++k) \
;         acc[ai][bj][m][n] = __builtin_amdgcn_mfma_f32_16x16x32_bf16(Bt[n][k], At[m][k], acc[ai][bj][m][n], 0, 0, 0); __builtin_amdgcn_s_setprio(0); } while (0)
; #define PG8_WAIT_V(n) asm volatile("s_waitcnt vmcnt(" #n ")" ::: "memory")
; #define PG8_WAIT_L(n) asm volatile("s_waitcnt lgkmcnt(" #n ")" ::: "memory")
; #define PG8_BAR __builtin_amdgcn_s_barrier()
; #define PG8_SCHED __builtin_amdgcn_sched_barrier(0)
; template <class Epi, class Sched, bool ALIGN_EPI = false, bool SP2 = false>
; __device__ __forceinline__ void gemm_phase(PG8_LAS unsigned char* lds, const Gemm g, const Sched& S, const Epi& E) {
;     ...
;             PG8_WAIT_V(8); PG8_WAIT_L(0); PG8_BAR; PG8_MMA(1, 0, At, B0); PG8_MMA(1, 1, At, B1); PG8_BAR; PG8_SCHED;
;             PG8_LDB(B0, 1, 0); PG8_LDB(B1, 1, 1); PG8_SCHED; PG8_LDA(At, 1, 0); PG8_STAGE(PG8_SA(0, 1), a2 + hstep, voffA);
;             PG8_WAIT_V(8); PG8_WAIT_L(0); PG8_BAR; PG8_MMA(0, 0, At, B0); PG8_MMA(0, 1, At, B1); PG8_BAR; PG8_SCHED;
	s_waitcnt lgkmcnt(0)
	v_mfma_f32_16x16x32_bf16 v[66:69], v[144:147], v[188:191], v[66:69]
	v_mfma_f32_16x16x32_bf16 v[58:61], v[164:167], v[188:191], v[58:61]
	v_mfma_f32_16x16x32_bf16 v[46:49], v[144:147], v[196:199], v[46:49]
	v_mfma_f32_16x16x32_bf16 v[42:45], v[164:167], v[196:199], v[42:45]
	v_mfma_f32_16x16x32_bf16 v[30:33], v[144:147], v[204:207], v[30:33]
	v_mfma_f32_16x16x32_bf16 v[26:29], v[164:167], v[204:207], v[26:29]
	v_mfma_f32_16x16x32_bf16 v[14:17], v[144:147], v[212:215], v[14:17]
	v_mfma_f32_16x16x32_bf16 v[10:13], v[164:167], v[212:215], v[10:13]
	v_mfma_f32_16x16x32_bf16 v[66:69], v[160:163], v[192:195], v[66:69]
	v_mfma_f32_16x16x32_bf16 v[58:61], v[168:171], v[192:195], v[58:61]
	v_mfma_f32_16x16x32_bf16 v[46:49], v[160:163], v[200:203], v[46:49]
	v_mfma_f32_16x16x32_bf16 v[42:45], v[168:171], v[200:203], v[42:45]
	v_mfma_f32_16x16x32_bf16 v[30:33], v[160:163], v[208:211], v[30:33]
	v_mfma_f32_16x16x32_bf16 v[26:29], v[168:171], v[208:211], v[26:29]
	v_mfma_f32_16x16x32_bf16 v[14:17], v[160:163], v[216:219], v[14:17]
	v_mfma_f32_16x16x32_bf16 v[10:13], v[168:171], v[216:219], v[10:13]
	v_mfma_f32_16x16x32_bf16 v[54:57], v[172:175], v[188:191], v[54:57]
	v_mfma_f32_16x16x32_bf16 v[50:53], v[180:183], v[188:191], v[50:53]
	v_mfma_f32_16x16x32_bf16 v[38:41], v[172:175], v[196:199], v[38:41]
	v_mfma_f32_16x16x32_bf16 v[34:37], v[180:183], v[196:199], v[34:37]
	v_mfma_f32_16x16x32_bf16 v[22:25], v[172:175], v[204:207], v[22:25]
	v_mfma_f32_16x16x32_bf16 v[18:21], v[180:183], v[204:207], v[18:21]
	v_mfma_f32_16x16x32_bf16 v[6:9], v[172:175], v[212:215], v[6:9]
	v_mfma_f32_16x16x32_bf16 v[2:5], v[180:183], v[212:215], v[2:5]
	v_mfma_f32_16x16x32_bf16 v[54:57], v[176:179], v[192:195], v[54:57]
	v_mfma_f32_16x16x32_bf16 v[50:53], v[184:187], v[192:195], v[50:53]
	v_mfma_f32_16x16x32_bf16 v[38:41], v[176:179], v[200:203], v[38:41]
	v_mfma_f32_16x16x32_bf16 v[34:37], v[184:187], v[200:203], v[34:37]
	v_mfma_f32_16x16x32_bf16 v[22:25], v[176:179], v[208:211], v[22:25]
	v_mfma_f32_16x16x32_bf16 v[18:21], v[184:187], v[208:211], v[18:21]
	v_mfma_f32_16x16x32_bf16 v[6:9], v[176:179], v[216:219], v[6:9]
	v_mfma_f32_16x16x32_bf16 v[2:5], v[184:187], v[216:219], v[2:5]
	s_barrier
	s_add_i32 s82, 0, 0x18000
	v_add_u32_e32 v134, s82, v156
	s_add_i32 s83, 0, 0x1c000
	ds_read_b128 v[144:147], v134
	ds_read_b128 v[160:163], v134 offset:1024
	ds_read_b128 v[164:167], v134 offset:2048
	ds_read_b128 v[168:171], v134 offset:3072
	v_add_u32_e32 v134, s83, v156
	ds_read_b128 v[172:175], v134
	ds_read_b128 v[176:179], v134 offset:1024
	ds_read_b128 v[180:183], v134 offset:2048
	ds_read_b128 v[184:187], v134 offset:3072
	s_add_u32 s64, s64, 0x40000
	s_addc_u32 s65, s65, 0
	s_mov_b32 m0, s68
	v_lshl_add_u64 v[228:229], s[64:65], 0, v[130:131]
	ds_read_b128 v[188:191], v158 offset:32768
	ds_read_b128 v[192:195], v158 offset:33792
	ds_read_b128 v[196:199], v158 offset:34816
	ds_read_b128 v[200:203], v158 offset:35840
	ds_read_b128 v[204:207], v158 offset:36864
	ds_read_b128 v[208:211], v158 offset:37888
	ds_read_b128 v[212:215], v158 offset:38912
	ds_read_b128 v[216:219], v158 offset:39936
	global_load_lds_dwordx4 v[228:229], off
	v_lshl_add_u64 v[228:229], s[64:65], 0, v[132:133]
	s_mov_b32 m0, s69
	s_nop 0
	global_load_lds_dwordx4 v[228:229], off
	s_waitcnt vmcnt(8)
	s_waitcnt lgkmcnt(0)
	s_barrier
	s_waitcnt lgkmcnt(0)
	v_mfma_f32_16x16x32_bf16 v[126:129], v[144:147], v[188:191], v[126:129]
	v_mfma_f32_16x16x32_bf16 v[122:125], v[164:167], v[188:191], v[122:125]
	v_mfma_f32_16x16x32_bf16 v[110:113], v[144:147], v[196:199], v[110:113]
	v_mfma_f32_16x16x32_bf16 v[106:109], v[164:167], v[196:199], v[106:109]
	v_mfma_f32_16x16x32_bf16 v[94:97], v[144:147], v[204:207], v[94:97]
	v_mfma_f32_16x16x32_bf16 v[90:93], v[164:167], v[204:207], v[90:93]
	v_mfma_f32_16x16x32_bf16 v[78:81], v[144:147], v[212:215], v[78:81]
	v_mfma_f32_16x16x32_bf16 v[74:77], v[164:167], v[212:215], v[74:77]
	v_mfma_f32_16x16x32_bf16 v[126:129], v[160:163], v[192:195], v[126:129]
	v_mfma_f32_16x16x32_bf16 v[122:125], v[168:171], v[192:195], v[122:125]
	v_mfma_f32_16x16x32_bf16 v[110:113], v[160:163], v[200:203], v[110:113]
	v_mfma_f32_16x16x32_bf16 v[106:109], v[168:171], v[200:203], v[106:109]
	v_mfma_f32_16x16x32_bf16 v[94:97], v[160:163], v[208:211], v[94:97]
	v_mfma_f32_16x16x32_bf16 v[90:93], v[168:171], v[208:211], v[90:93]
	v_mfma_f32_16x16x32_bf16 v[78:81], v[160:163], v[216:219], v[78:81]
	v_mfma_f32_16x16x32_bf16 v[74:77], v[168:171], v[216:219], v[74:77]
	v_mfma_f32_16x16x32_bf16 v[118:121], v[172:175], v[188:191], v[118:121]
	v_mfma_f32_16x16x32_bf16 v[114:117], v[180:183], v[188:191], v[114:117]
	v_mfma_f32_16x16x32_bf16 v[102:105], v[172:175], v[196:199], v[102:105]
	v_mfma_f32_16x16x32_bf16 v[98:101], v[180:183], v[196:199], v[98:101]
	v_mfma_f32_16x16x32_bf16 v[86:89], v[172:175], v[204:207], v[86:89]
	v_mfma_f32_16x16x32_bf16 v[82:85], v[180:183], v[204:207], v[82:85]
	v_mfma_f32_16x16x32_bf16 v[70:73], v[172:175], v[212:215], v[70:73]
	v_mfma_f32_16x16x32_bf16 v[62:65], v[180:183], v[212:215], v[62:65]
	v_mfma_f32_16x16x32_bf16 v[118:121], v[176:179], v[192:195], v[118:121]
	v_mfma_f32_16x16x32_bf16 v[114:117], v[184:187], v[192:195], v[114:117]
	v_mfma_f32_16x16x32_bf16 v[102:105], v[176:179], v[200:203], v[102:105]
	v_mfma_f32_16x16x32_bf16 v[98:101], v[184:187], v[200:203], v[98:101]
	v_mfma_f32_16x16x32_bf16 v[86:89], v[176:179], v[208:211], v[86:89]
	v_mfma_f32_16x16x32_bf16 v[82:85], v[184:187], v[208:211], v[82:85]
	v_mfma_f32_16x16x32_bf16 v[70:73], v[176:179], v[216:219], v[70:73]
	v_mfma_f32_16x16x32_bf16 v[62:65], v[184:187], v[216:219], v[62:65]
	s_barrier
; #define PG8_STAGE(bufoff, gbase, voff) do { _Pragma("unroll") for (int _i = 0; _i < 2; ++_i) \
;         __builtin_amdgcn_global_load_lds((const unsigned*)((const char*)(gbase) + (voff)[_i]), (PG8_LAS unsigned*)(lds + (bufoff) + ldsw + _i * 8192), 16, 0, 0); } while (0)
; #define PG8_LDA(dst, b, h) do { _Pragma("unroll") for (int m = 0; m < 4; ++m) _Pragma("unroll") for (int k = 0; k < 2; ++k) dst[m][k] = *(const PG8_LAS bf16x8*)(lds + PG8_SA(b, h) + aoff + m * 2048 + k * 1024); } while (0)
; #define PG8_MMA(ai, bj, At, Bt) do { __builtin_amdgcn_s_setprio(1); _Pragma("unroll") for (int m = 0; m < 4; ++m) _Pragma("unroll") for (int n = 0; n < 2; ++n) _Pragma("unroll") for (int k = 0; k < 2; ++k) \
;         acc[ai][bj][m][n] = __builtin_amdgcn_mfma_f32_16x16x32_bf16(Bt[n][k], At[m][k], acc[ai][bj][m][n], 0, 0, 0); __builtin_amdgcn_s_setprio(0); } while (0)
; #define PG8_WAIT_V(n) asm volatile("s_waitcnt vmcnt(" #n ")" ::: "memory")
; #define PG8_WAIT_L(n) asm volatile("s_waitcnt lgkmcnt(" #n ")" ::: "memory")
; #define PG8_BAR __builtin_amdgcn_s_barrier()
; #define PG8_SCHED __builtin_amdgcn_sched_barrier(0)
; template <class Epi, class Sched, bool ALIGN_EPI = false, bool SP2 = false>
; __device__ __forceinline__ void gemm_phase(PG8_LAS unsigned char* lds, const Gemm g, const Sched& S, const Epi& E) {
;     ...
;         for (int t = 0; t < nt; t += 2) {
;             const bool last = (t == nt - 2);
;             const char* a1 = cA + (size_t)(t + 1) * kstep;
;             const char* a2 = last ? nA : cA + (size_t)(t + 2) * kstep; const char* b2 = last ? nB : cB + (size_t)(t + 2) * kstep;
;     ...
;             PG8_LDA(At, 1, 1); PG8_STAGE(PG8_SB(1, 0), b3, voffB); PG8_STAGE(PG8_SB(1, 1), b3 + hstep, voffB); PG8_STAGE(PG8_SA(1, 0), a3, voffA);
;             PG8_WAIT_V(8); PG8_WAIT_L(0); PG8_BAR; PG8_MMA(1, 0, At, B0); PG8_MMA(1, 1, At, B1); PG8_BAR; PG8_SCHED;
	s_add_i32 s64, s82, s66
	v_lshl_add_u64 v[220:221], v[220:221], 0, s[20:21]
	s_mov_b32 m0, s64
	ds_read_b128 v[188:191], v158 offset:49152
	ds_read_b128 v[192:195], v158 offset:50176
	ds_read_b128 v[196:199], v158 offset:51200
	ds_read_b128 v[200:203], v158 offset:52224
	ds_read_b128 v[204:207], v158 offset:53248
	ds_read_b128 v[208:211], v158 offset:54272
	ds_read_b128 v[212:215], v158 offset:55296
	ds_read_b128 v[216:219], v158 offset:56320
	global_load_lds_dwordx4 v[220:221], off
	s_add_i32 m0, s64, 0x2000
	s_add_u32 s62, s62, 0x40080
	v_lshl_add_u64 v[220:221], v[222:223], 0, s[20:21]
	s_addc_u32 s63, s63, 0
	s_add_i32 s64, s83, s66
	global_load_lds_dwordx4 v[220:221], off
	v_lshl_add_u64 v[220:221], s[62:63], 0, v[130:131]
	s_mov_b32 m0, s64
	s_nop 0
	global_load_lds_dwordx4 v[220:221], off
	v_lshl_add_u64 v[220:221], s[62:63], 0, v[132:133]
	s_add_i32 m0, s64, 0x2000
	s_nop 0
	global_load_lds_dwordx4 v[220:221], off
	v_lshl_add_u64 v[220:221], v[224:225], 0, s[20:21]
	s_mov_b32 m0, s70
	s_nop 0
	global_load_lds_dwordx4 v[220:221], off
	v_lshl_add_u64 v[220:221], v[226:227], 0, s[20:21]
	s_mov_b32 m0, s71
	s_nop 0
	global_load_lds_dwordx4 v[220:221], off
	s_waitcnt vmcnt(8)
	s_waitcnt lgkmcnt(0)
	s_barrier
	s_waitcnt lgkmcnt(0)
	v_mfma_f32_16x16x32_bf16 v[66:69], v[144:147], v[188:191], v[66:69]
	v_mfma_f32_16x16x32_bf16 v[58:61], v[164:167], v[188:191], v[58:61]
	v_mfma_f32_16x16x32_bf16 v[46:49], v[144:147], v[196:199], v[46:49]
	v_mfma_f32_16x16x32_bf16 v[42:45], v[164:167], v[196:199], v[42:45]
	v_mfma_f32_16x16x32_bf16 v[30:33], v[144:147], v[204:207], v[30:33]
	v_mfma_f32_16x16x32_bf16 v[26:29], v[164:167], v[204:207], v[26:29]
	v_mfma_f32_16x16x32_bf16 v[14:17], v[144:147], v[212:215], v[14:17]
	v_mfma_f32_16x16x32_bf16 v[10:13], v[164:167], v[212:215], v[10:13]
	v_mfma_f32_16x16x32_bf16 v[66:69], v[160:163], v[192:195], v[66:69]
	v_mfma_f32_16x16x32_bf16 v[58:61], v[168:171], v[192:195], v[58:61]
	v_mfma_f32_16x16x32_bf16 v[46:49], v[160:163], v[200:203], v[46:49]
	v_mfma_f32_16x16x32_bf16 v[42:45], v[168:171], v[200:203], v[42:45]
	v_mfma_f32_16x16x32_bf16 v[30:33], v[160:163], v[208:211], v[30:33]
	v_mfma_f32_16x16x32_bf16 v[26:29], v[168:171], v[208:211], v[26:29]
	v_mfma_f32_16x16x32_bf16 v[14:17], v[160:163], v[216:219], v[14:17]
	v_mfma_f32_16x16x32_bf16 v[10:13], v[168:171], v[216:219], v[10:13]
	v_mfma_f32_16x16x32_bf16 v[54:57], v[172:175], v[188:191], v[54:57]
	v_mfma_f32_16x16x32_bf16 v[50:53], v[180:183], v[188:191], v[50:53]
	v_mfma_f32_16x16x32_bf16 v[38:41], v[172:175], v[196:199], v[38:41]
	v_mfma_f32_16x16x32_bf16 v[34:37], v[180:183], v[196:199], v[34:37]
	v_mfma_f32_16x16x32_bf16 v[22:25], v[172:175], v[204:207], v[22:25]
	v_mfma_f32_16x16x32_bf16 v[18:21], v[180:183], v[204:207], v[18:21]
	v_mfma_f32_16x16x32_bf16 v[6:9], v[172:175], v[212:215], v[6:9]
	v_mfma_f32_16x16x32_bf16 v[2:5], v[180:183], v[212:215], v[2:5]
	v_mfma_f32_16x16x32_bf16 v[54:57], v[176:179], v[192:195], v[54:57]
	v_mfma_f32_16x16x32_bf16 v[50:53], v[184:187], v[192:195], v[50:53]
	v_mfma_f32_16x16x32_bf16 v[38:41], v[176:179], v[200:203], v[38:41]
	v_mfma_f32_16x16x32_bf16 v[34:37], v[184:187], v[200:203], v[34:37]
	v_mfma_f32_16x16x32_bf16 v[22:25], v[176:179], v[208:211], v[22:25]
	v_mfma_f32_16x16x32_bf16 v[18:21], v[184:187], v[208:211], v[18:21]
	v_mfma_f32_16x16x32_bf16 v[6:9], v[176:179], v[216:219], v[6:9]
	v_mfma_f32_16x16x32_bf16 v[2:5], v[184:187], v[216:219], v[2:5]
	s_barrier
	s_add_i32 s81, s81, 2
	s_add_u32 s0, s0, 0x100
	s_addc_u32 s1, s1, 0
	s_add_u32 s79, s79, 0x100
	s_addc_u32 s80, s80, 0
	s_cmp_gt_u32 s81, 13
	s_cbranch_scc0 .LBB0_775
	s_and_b64 vcc, exec, s[28:29]
	s_cbranch_vccz .LBB0_778
	s_barrier

; #define PG8_STAGE(bufoff, gbase, voff) do { _Pragma("unroll") for (int _i = 0; _i < 2; ++_i) \
;         __builtin_amdgcn_global_load_lds((const unsigned*)((const char*)(gbase) + (voff)[_i]), (PG8_LAS unsigned*)(lds + (bufoff) + ldsw + _i * 8192), 16, 0, 0); } while (0)
; #define PG8_LDA(dst, b, h) do { _Pragma("unroll") for (int m = 0; m < 4; ++m) _Pragma("unroll") for (int k = 0; k < 2; ++k) dst[m][k] = *(const PG8_LAS bf16x8*)(lds + PG8_SA(b, h) + aoff + m * 2048 + k * 1024); } while (0)
; #define PG8_LDB(dst, b, h) do { _Pragma("unroll") for (int n = 0; n < 2; ++n) _Pragma("unroll") for (int k = 0; k < 2; ++k) dst[n][k] = *(const PG8_LAS bf16x8*)(lds + PG8_SB(b, h) + boff + n * 2048 + k * 1024); } while (0)
; #define PG8_MMA(ai, bj, At, Bt) do { __builtin_amdgcn_s_setprio(1); _Pragma("unroll") for (int m = 0; m < 4; ++m) _Pragma("unroll") for (int n = 0; n < 2; ++n) _Pragma("unroll") for (int k = 0; k < 2; ++k) \
;         acc[ai][bj][m][n] = __builtin_amdgcn_mfma_f32_16x16x32_bf16(Bt[n][k], At[m][k], acc[ai][bj][m][n], 0, 0, 0); __builtin_amdgcn_s_setprio(0); } while (0)
; #define PG8_WAIT_V(n) asm volatile("s_waitcnt vmcnt(" #n ")" ::: "memory")
; #define PG8_WAIT_L(n) asm volatile("s_waitcnt lgkmcnt(" #n ")" ::: "memory")
; #define PG8_BAR __builtin_amdgcn_s_barrier()
; #define PG8_SCHED __builtin_amdgcn_sched_barrier(0)
; template <class Epi, class Sched, bool ALIGN_EPI = false, bool SP2 = false>
; __device__ __forceinline__ void gemm_phase(PG8_LAS unsigned char* lds, const Gemm g, const Sched& S, const Epi& E) {
;     ...
;             PG8_LDB(B0, 0, 0); PG8_LDB(B1, 0, 1); PG8_SCHED; PG8_LDA(At, 0, 0); PG8_STAGE(PG8_SA(1, 1), a1 + hstep, voffA);
;             PG8_WAIT_V(8); PG8_WAIT_L(0); PG8_BAR; PG8_MMA(0, 0, At, B0); PG8_MMA(0, 1, At, B1); PG8_BAR; PG8_SCHED;
;             PG8_LDA(At, 0, 1); PG8_STAGE(PG8_SB(0, 0), b2, voffB); PG8_STAGE(PG8_SB(0, 1), b2 + hstep, voffB); PG8_STAGE(PG8_SA(0, 0), a2, voffA);
;             PG8_WAIT_V(8); PG8_WAIT_L(0); PG8_BAR; PG8_MMA(1, 0, At, B0); PG8_MMA(1, 1, At, B1); PG8_BAR; PG8_SCHED;
.LBB0_866:
	ds_read_b128 v[142:145], v148
	ds_read_b128 v[152:155], v148 offset:1024
	ds_read_b128 v[156:159], v148 offset:2048
	ds_read_b128 v[160:163], v148 offset:3072
	ds_read_b128 v[164:167], v149
	ds_read_b128 v[168:171], v149 offset:1024
	ds_read_b128 v[172:175], v149 offset:2048
	ds_read_b128 v[176:179], v149 offset:3072
	s_add_u32 s0, s48, 0xfffc0080
	s_addc_u32 s1, s49, -1
	s_cmp_eq_u32 s75, 12
	s_cselect_b32 s51, s21, s1
	s_cselect_b32 s50, s71, s0
	s_cselect_b32 s1, s19, s74
	s_cselect_b32 s0, s72, s73
	v_lshl_add_u64 v[212:213], s[48:49], 0, v[134:135]
	s_add_i32 m0, s35, 0xc000
	ds_read_b128 v[180:183], v150
	ds_read_b128 v[184:187], v150 offset:1024
	ds_read_b128 v[188:191], v150 offset:2048
	ds_read_b128 v[192:195], v150 offset:3072
	ds_read_b128 v[196:199], v150 offset:4096
	ds_read_b128 v[200:203], v150 offset:5120
	ds_read_b128 v[204:207], v150 offset:6144
	ds_read_b128 v[208:211], v150 offset:7168
	global_load_lds_dwordx4 v[212:213], off
	v_lshl_add_u64 v[212:213], s[48:49], 0, v[136:137]
	s_add_i32 m0, s35, 0xe000
	s_nop 0
	global_load_lds_dwordx4 v[212:213], off
	s_waitcnt vmcnt(8)
	s_waitcnt lgkmcnt(0)
	s_barrier
	s_waitcnt lgkmcnt(0)
	v_mfma_f32_16x16x32_bf16 v[126:129], v[142:145], v[180:183], v[126:129]
	v_mfma_f32_16x16x32_bf16 v[122:125], v[156:159], v[180:183], v[122:125]
	v_mfma_f32_16x16x32_bf16 v[110:113], v[142:145], v[188:191], v[110:113]
	v_mfma_f32_16x16x32_bf16 v[106:109], v[156:159], v[188:191], v[106:109]
	v_mfma_f32_16x16x32_bf16 v[94:97], v[142:145], v[196:199], v[94:97]
	v_mfma_f32_16x16x32_bf16 v[90:93], v[156:159], v[196:199], v[90:93]
	v_mfma_f32_16x16x32_bf16 v[78:81], v[142:145], v[204:207], v[78:81]
	v_mfma_f32_16x16x32_bf16 v[74:77], v[156:159], v[204:207], v[74:77]
	v_mfma_f32_16x16x32_bf16 v[126:129], v[152:155], v[184:187], v[126:129]
	v_mfma_f32_16x16x32_bf16 v[122:125], v[160:163], v[184:187], v[122:125]
	v_mfma_f32_16x16x32_bf16 v[110:113], v[152:155], v[192:195], v[110:113]
	v_mfma_f32_16x16x32_bf16 v[106:109], v[160:163], v[192:195], v[106:109]
	v_mfma_f32_16x16x32_bf16 v[94:97], v[152:155], v[200:203], v[94:97]
	v_mfma_f32_16x16x32_bf16 v[90:93], v[160:163], v[200:203], v[90:93]
	v_mfma_f32_16x16x32_bf16 v[78:81], v[152:155], v[208:211], v[78:81]
	v_mfma_f32_16x16x32_bf16 v[74:77], v[160:163], v[208:211], v[74:77]
	v_mfma_f32_16x16x32_bf16 v[118:121], v[164:167], v[180:183], v[118:121]
	v_mfma_f32_16x16x32_bf16 v[114:117], v[172:175], v[180:183], v[114:117]
	v_mfma_f32_16x16x32_bf16 v[102:105], v[164:167], v[188:191], v[102:105]
	v_mfma_f32_16x16x32_bf16 v[98:101], v[172:175], v[188:191], v[98:101]
	v_mfma_f32_16x16x32_bf16 v[86:89], v[164:167], v[196:199], v[86:89]
	v_mfma_f32_16x16x32_bf16 v[82:85], v[172:175], v[196:199], v[82:85]
	v_mfma_f32_16x16x32_bf16 v[70:73], v[164:167], v[204:207], v[70:73]
	v_mfma_f32_16x16x32_bf16 v[66:69], v[172:175], v[204:207], v[66:69]
	v_mfma_f32_16x16x32_bf16 v[118:121], v[168:171], v[184:187], v[118:121]
	v_mfma_f32_16x16x32_bf16 v[114:117], v[176:179], v[184:187], v[114:117]
	v_mfma_f32_16x16x32_bf16 v[102:105], v[168:171], v[192:195], v[102:105]
	v_mfma_f32_16x16x32_bf16 v[98:101], v[176:179], v[192:195], v[98:101]
	v_mfma_f32_16x16x32_bf16 v[86:89], v[168:171], v[200:203], v[86:89]
	v_mfma_f32_16x16x32_bf16 v[82:85], v[176:179], v[200:203], v[82:85]
	v_mfma_f32_16x16x32_bf16 v[70:73], v[168:171], v[208:211], v[70:73]
	v_mfma_f32_16x16x32_bf16 v[66:69], v[176:179], v[208:211], v[66:69]
	s_barrier
	s_add_i32 s76, s67, s52
	v_lshl_add_u64 v[212:213], s[0:1], 0, v[130:131]
	s_mov_b32 m0, s76
	ds_read_b128 v[180:183], v150 offset:16384
	ds_read_b128 v[184:187], v150 offset:17408
	ds_read_b128 v[188:191], v150 offset:18432
	ds_read_b128 v[192:195], v150 offset:19456
	ds_read_b128 v[196:199], v150 offset:20480
	ds_read_b128 v[200:203], v150 offset:21504
	ds_read_b128 v[204:207], v150 offset:22528
	ds_read_b128 v[208:211], v150 offset:23552
	global_load_lds_dwordx4 v[212:213], off
	s_add_i32 m0, s76, 0x2000
	s_add_u32 s76, s0, 0x40000
	v_lshl_add_u64 v[214:215], s[0:1], 0, v[132:133]
	s_addc_u32 s77, s1, 0
	s_add_i32 s78, s68, s52
	global_load_lds_dwordx4 v[214:215], off
	v_lshl_add_u64 v[216:217], s[76:77], 0, v[130:131]
	s_mov_b32 m0, s78
	v_lshl_add_u64 v[218:219], s[50:51], 0, v[132:133]
	global_load_lds_dwordx4 v[216:217], off
	v_lshl_add_u64 v[216:217], s[76:77], 0, v[132:133]
	s_add_i32 m0, s78, 0x2000
	s_nop 0
	global_load_lds_dwordx4 v[216:217], off
	v_lshl_add_u64 v[216:217], s[50:51], 0, v[130:131]
	s_mov_b32 m0, s35
	s_nop 0
	global_load_lds_dwordx4 v[216:217], off
	s_mov_b32 m0, s53
	s_nop 0
	global_load_lds_dwordx4 v[218:219], off
	s_waitcnt vmcnt(8)
	s_waitcnt lgkmcnt(0)
	s_barrier
; #define PG8_STAGE(bufoff, gbase, voff) do { _Pragma("unroll") for (int _i = 0; _i < 2; ++_i) \
;         __builtin_amdgcn_global_load_lds((const unsigned*)((const char*)(gbase) + (voff)[_i]), (PG8_LAS unsigned*)(lds + (bufoff) + ldsw + _i * 8192), 16, 0, 0); } while (0)
; #define PG8_LDA(dst, b, h) do { _Pragma("unroll") for (int m = 0; m < 4; ++m) _Pragma("unroll") for (int k = 0; k < 2; ++k) dst[m][k] = *(const PG8_LAS bf16x8*)(lds + PG8_SA(b, h) + aoff + m * 2048 + k * 1024); } while (0)
; #define PG8_LDB(dst, b, h) do { _Pragma("unroll") for (int n = 0; n < 2; ++n) _Pragma("unroll") for (int k = 0; k < 2; ++k) dst[n][k] = *(const PG8_LAS bf16x8*)(lds + PG8_SB(b, h) + boff + n * 2048 + k * 1024); } while (0)
; #define PG8_MMA(ai, bj, At, Bt) do { __builtin_amdgcn_s_setprio(1); _Pragma("unroll") for (int m = 0; m < 4; ++m) _Pragma("unroll") for (int n = 0; n < 2; ++n) _Pragma("unroll") for (int k = 0; k < 2; ++k) \
;         acc[ai][bj][m][n] = __builtin_amdgcn_mfma_f32_16x16x32_bf16(Bt[n][k], At[m][k], acc[ai][bj][m][n], 0, 0, 0); __builtin_amdgcn_s_setprio(0); } while (0)
; #define PG8_WAIT_V(n) asm volatile("s_waitcnt vmcnt(" #n ")" ::: "memory")
; #define PG8_WAIT_L(n) asm volatile("s_waitcnt lgkmcnt(" #n ")" ::: "memory")
; #define PG8_BAR __builtin_amdgcn_s_barrier()
; #define PG8_SCHED __builtin_amdgcn_sched_barrier(0)
; template <class Epi, class Sched, bool ALIGN_EPI = false, bool SP2 = false>
; __device__ __forceinline__ void gemm_phase(PG8_LAS unsigned char* lds, const Gemm g, const Sched& S, const Epi& E) {
;     ...
;             PG8_WAIT_V(8); PG8_WAIT_L(0); PG8_BAR; PG8_MMA(1, 0, At, B0); PG8_MMA(1, 1, At, B1); PG8_BAR; PG8_SCHED;
;             PG8_LDB(B0, 1, 0); PG8_LDB(B1, 1, 1); PG8_SCHED; PG8_LDA(At, 1, 0); PG8_STAGE(PG8_SA(0, 1), a2 + hstep, voffA);
;             PG8_WAIT_V(8); PG8_WAIT_L(0); PG8_BAR; PG8_MMA(0, 0, At, B0); PG8_MMA(0, 1, At, B1); PG8_BAR; PG8_SCHED;
	s_waitcnt lgkmcnt(0)
	v_mfma_f32_16x16x32_bf16 v[62:65], v[142:145], v[180:183], v[62:65]
	v_mfma_f32_16x16x32_bf16 v[58:61], v[156:159], v[180:183], v[58:61]
	v_mfma_f32_16x16x32_bf16 v[46:49], v[142:145], v[188:191], v[46:49]
	v_mfma_f32_16x16x32_bf16 v[42:45], v[156:159], v[188:191], v[42:45]
	v_mfma_f32_16x16x32_bf16 v[30:33], v[142:145], v[196:199], v[30:33]
	v_mfma_f32_16x16x32_bf16 v[26:29], v[156:159], v[196:199], v[26:29]
	v_mfma_f32_16x16x32_bf16 v[14:17], v[142:145], v[204:207], v[14:17]
	v_mfma_f32_16x16x32_bf16 v[10:13], v[156:159], v[204:207], v[10:13]
	v_mfma_f32_16x16x32_bf16 v[62:65], v[152:155], v[184:187], v[62:65]
	v_mfma_f32_16x16x32_bf16 v[58:61], v[160:163], v[184:187], v[58:61]
	v_mfma_f32_16x16x32_bf16 v[46:49], v[152:155], v[192:195], v[46:49]
	v_mfma_f32_16x16x32_bf16 v[42:45], v[160:163], v[192:195], v[42:45]
	v_mfma_f32_16x16x32_bf16 v[30:33], v[152:155], v[200:203], v[30:33]
	v_mfma_f32_16x16x32_bf16 v[26:29], v[160:163], v[200:203], v[26:29]
	v_mfma_f32_16x16x32_bf16 v[14:17], v[152:155], v[208:211], v[14:17]
	v_mfma_f32_16x16x32_bf16 v[10:13], v[160:163], v[208:211], v[10:13]
	v_mfma_f32_16x16x32_bf16 v[54:57], v[164:167], v[180:183], v[54:57]
	v_mfma_f32_16x16x32_bf16 v[50:53], v[172:175], v[180:183], v[50:53]
	v_mfma_f32_16x16x32_bf16 v[38:41], v[164:167], v[188:191], v[38:41]
	v_mfma_f32_16x16x32_bf16 v[34:37], v[172:175], v[188:191], v[34:37]
	v_mfma_f32_16x16x32_bf16 v[22:25], v[164:167], v[196:199], v[22:25]
	v_mfma_f32_16x16x32_bf16 v[18:21], v[172:175], v[196:199], v[18:21]
	v_mfma_f32_16x16x32_bf16 v[6:9], v[164:167], v[204:207], v[6:9]
	v_mfma_f32_16x16x32_bf16 v[2:5], v[172:175], v[204:207], v[2:5]
	v_mfma_f32_16x16x32_bf16 v[54:57], v[168:171], v[184:187], v[54:57]
	v_mfma_f32_16x16x32_bf16 v[50:53], v[176:179], v[184:187], v[50:53]
	v_mfma_f32_16x16x32_bf16 v[38:41], v[168:171], v[192:195], v[38:41]
	v_mfma_f32_16x16x32_bf16 v[34:37], v[176:179], v[192:195], v[34:37]
	v_mfma_f32_16x16x32_bf16 v[22:25], v[168:171], v[200:203], v[22:25]
	v_mfma_f32_16x16x32_bf16 v[18:21], v[176:179], v[200:203], v[18:21]
	v_mfma_f32_16x16x32_bf16 v[6:9], v[168:171], v[208:211], v[6:9]
	v_mfma_f32_16x16x32_bf16 v[2:5], v[176:179], v[208:211], v[2:5]
	s_barrier
	s_add_i32 s76, 0, 0x18000
	s_add_i32 s77, 0, 0x1c000
	v_add_u32_e32 v160, s76, v146
	v_add_u32_e32 v176, s77, v146
	ds_read_b128 v[142:145], v160
	ds_read_b128 v[152:155], v160 offset:1024
	ds_read_b128 v[156:159], v160 offset:2048
	ds_read_b128 v[160:163], v160 offset:3072
	ds_read_b128 v[164:167], v176
	ds_read_b128 v[168:171], v176 offset:1024
	ds_read_b128 v[172:175], v176 offset:2048
	ds_read_b128 v[176:179], v176 offset:3072
	s_add_u32 s50, s50, 0x40000
	s_addc_u32 s51, s51, 0
	s_mov_b32 m0, s56
	v_lshl_add_u64 v[220:221], s[50:51], 0, v[130:131]
	ds_read_b128 v[180:183], v150 offset:32768
	ds_read_b128 v[184:187], v150 offset:33792
	ds_read_b128 v[188:191], v150 offset:34816
	ds_read_b128 v[192:195], v150 offset:35840
	ds_read_b128 v[196:199], v150 offset:36864
	ds_read_b128 v[200:203], v150 offset:37888
	ds_read_b128 v[204:207], v150 offset:38912
	ds_read_b128 v[208:211], v150 offset:39936
	global_load_lds_dwordx4 v[220:221], off
	v_lshl_add_u64 v[220:221], s[50:51], 0, v[132:133]
	s_mov_b32 m0, s57
	s_nop 0
	global_load_lds_dwordx4 v[220:221], off
	s_waitcnt vmcnt(8)
	s_waitcnt lgkmcnt(0)
	s_barrier
	s_waitcnt lgkmcnt(0)
	v_mfma_f32_16x16x32_bf16 v[126:129], v[142:145], v[180:183], v[126:129]
	v_mfma_f32_16x16x32_bf16 v[122:125], v[156:159], v[180:183], v[122:125]
	v_mfma_f32_16x16x32_bf16 v[110:113], v[142:145], v[188:191], v[110:113]
	v_mfma_f32_16x16x32_bf16 v[106:109], v[156:159], v[188:191], v[106:109]
	v_mfma_f32_16x16x32_bf16 v[94:97], v[142:145], v[196:199], v[94:97]
	v_mfma_f32_16x16x32_bf16 v[90:93], v[156:159], v[196:199], v[90:93]
	v_mfma_f32_16x16x32_bf16 v[78:81], v[142:145], v[204:207], v[78:81]
	v_mfma_f32_16x16x32_bf16 v[74:77], v[156:159], v[204:207], v[74:77]
	v_mfma_f32_16x16x32_bf16 v[126:129], v[152:155], v[184:187], v[126:129]
	v_mfma_f32_16x16x32_bf16 v[122:125], v[160:163], v[184:187], v[122:125]
	v_mfma_f32_16x16x32_bf16 v[110:113], v[152:155], v[192:195], v[110:113]
	v_mfma_f32_16x16x32_bf16 v[106:109], v[160:163], v[192:195], v[106:109]
	v_mfma_f32_16x16x32_bf16 v[94:97], v[152:155], v[200:203], v[94:97]
	v_mfma_f32_16x16x32_bf16 v[90:93], v[160:163], v[200:203], v[90:93]
	v_mfma_f32_16x16x32_bf16 v[78:81], v[152:155], v[208:211], v[78:81]
	v_mfma_f32_16x16x32_bf16 v[74:77], v[160:163], v[208:211], v[74:77]
	v_mfma_f32_16x16x32_bf16 v[118:121], v[164:167], v[180:183], v[118:121]
	v_mfma_f32_16x16x32_bf16 v[114:117], v[172:175], v[180:183], v[114:117]
	v_mfma_f32_16x16x32_bf16 v[102:105], v[164:167], v[188:191], v[102:105]
	v_mfma_f32_16x16x32_bf16 v[98:101], v[172:175], v[188:191], v[98:101]
	v_mfma_f32_16x16x32_bf16 v[86:89], v[164:167], v[196:199], v[86:89]
	v_mfma_f32_16x16x32_bf16 v[82:85], v[172:175], v[196:199], v[82:85]
	v_mfma_f32_16x16x32_bf16 v[70:73], v[164:167], v[204:207], v[70:73]
	v_mfma_f32_16x16x32_bf16 v[66:69], v[172:175], v[204:207], v[66:69]
	v_mfma_f32_16x16x32_bf16 v[118:121], v[168:171], v[184:187], v[118:121]
	v_mfma_f32_16x16x32_bf16 v[114:117], v[176:179], v[184:187], v[114:117]
	v_mfma_f32_16x16x32_bf16 v[102:105], v[168:171], v[192:195], v[102:105]
	v_mfma_f32_16x16x32_bf16 v[98:101], v[176:179], v[192:195], v[98:101]
	v_mfma_f32_16x16x32_bf16 v[86:89], v[168:171], v[200:203], v[86:89]
	v_mfma_f32_16x16x32_bf16 v[82:85], v[176:179], v[200:203], v[82:85]
	v_mfma_f32_16x16x32_bf16 v[70:73], v[168:171], v[208:211], v[70:73]
	v_mfma_f32_16x16x32_bf16 v[66:69], v[176:179], v[208:211], v[66:69]
	s_barrier
; #define PG8_STAGE(bufoff, gbase, voff) do { _Pragma("unroll") for (int _i = 0; _i < 2; ++_i) \
;         __builtin_amdgcn_global_load_lds((const unsigned*)((const char*)(gbase) + (voff)[_i]), (PG8_LAS unsigned*)(lds + (bufoff) + ldsw + _i * 8192), 16, 0, 0); } while (0)
; #define PG8_LDA(dst, b, h) do { _Pragma("unroll") for (int m = 0; m < 4; ++m) _Pragma("unroll") for (int k = 0; k < 2; ++k) dst[m][k] = *(const PG8_LAS bf16x8*)(lds + PG8_SA(b, h) + aoff + m * 2048 + k * 1024); } while (0)
; #define PG8_MMA(ai, bj, At, Bt) do { __builtin_amdgcn_s_setprio(1); _Pragma("unroll") for (int m = 0; m < 4; ++m) _Pragma("unroll") for (int n = 0; n < 2; ++n) _Pragma("unroll") for (int k = 0; k < 2; ++k) \
;         acc[ai][bj][m][n] = __builtin_amdgcn_mfma_f32_16x16x32_bf16(Bt[n][k], At[m][k], acc[ai][bj][m][n], 0, 0, 0); __builtin_amdgcn_s_setprio(0); } while (0)
; #define PG8_WAIT_V(n) asm volatile("s_waitcnt vmcnt(" #n ")" ::: "memory")
; #define PG8_WAIT_L(n) asm volatile("s_waitcnt lgkmcnt(" #n ")" ::: "memory")
; #define PG8_BAR __builtin_amdgcn_s_barrier()
; #define PG8_SCHED __builtin_amdgcn_sched_barrier(0)
; template <class Epi, class Sched, bool ALIGN_EPI = false, bool SP2 = false>
; __device__ __forceinline__ void gemm_phase(PG8_LAS unsigned char* lds, const Gemm g, const Sched& S, const Epi& E) {
;     ...
;         for (int t = 0; t < nt; t += 2) {
;             const bool last = (t == nt - 2);
;             const char* a1 = cA + (size_t)(t + 1) * kstep;
;             const char* a2 = last ? nA : cA + (size_t)(t + 2) * kstep; const char* b2 = last ? nB : cB + (size_t)(t + 2) * kstep;
;     ...
;             PG8_LDA(At, 1, 1); PG8_STAGE(PG8_SB(1, 0), b3, voffB); PG8_STAGE(PG8_SB(1, 1), b3 + hstep, voffB); PG8_STAGE(PG8_SA(1, 0), a3, voffA);
;             PG8_WAIT_V(8); PG8_WAIT_L(0); PG8_BAR; PG8_MMA(1, 0, At, B0); PG8_MMA(1, 1, At, B1); PG8_BAR; PG8_SCHED;
	s_add_i32 s50, s76, s52
	v_lshl_add_u64 v[212:213], v[212:213], 0, s[14:15]
	s_mov_b32 m0, s50
	ds_read_b128 v[180:183], v150 offset:49152
	ds_read_b128 v[184:187], v150 offset:50176
	ds_read_b128 v[188:191], v150 offset:51200
	ds_read_b128 v[192:195], v150 offset:52224
	ds_read_b128 v[196:199], v150 offset:53248
	ds_read_b128 v[200:203], v150 offset:54272
	ds_read_b128 v[204:207], v150 offset:55296
	ds_read_b128 v[208:211], v150 offset:56320
	global_load_lds_dwordx4 v[212:213], off
	s_add_i32 m0, s50, 0x2000
	s_add_u32 s0, s0, 0x40080
	v_lshl_add_u64 v[212:213], v[214:215], 0, s[14:15]
	s_addc_u32 s1, s1, 0
	s_add_i32 s50, s77, s52
	global_load_lds_dwordx4 v[212:213], off
	v_lshl_add_u64 v[212:213], s[0:1], 0, v[130:131]
	s_mov_b32 m0, s50
	s_nop 0
	global_load_lds_dwordx4 v[212:213], off
	v_lshl_add_u64 v[212:213], s[0:1], 0, v[132:133]
	s_add_i32 m0, s50, 0x2000
	s_nop 0
	global_load_lds_dwordx4 v[212:213], off
	v_lshl_add_u64 v[212:213], v[216:217], 0, s[14:15]
	s_mov_b32 m0, s64
	s_nop 0
	global_load_lds_dwordx4 v[212:213], off
	v_lshl_add_u64 v[212:213], v[218:219], 0, s[14:15]
	s_mov_b32 m0, s65
	s_nop 0
	global_load_lds_dwordx4 v[212:213], off
	s_waitcnt vmcnt(8)
	s_waitcnt lgkmcnt(0)
	s_barrier
	s_waitcnt lgkmcnt(0)
	v_mfma_f32_16x16x32_bf16 v[62:65], v[142:145], v[180:183], v[62:65]
	v_mfma_f32_16x16x32_bf16 v[58:61], v[156:159], v[180:183], v[58:61]
	v_mfma_f32_16x16x32_bf16 v[46:49], v[142:145], v[188:191], v[46:49]
	v_mfma_f32_16x16x32_bf16 v[42:45], v[156:159], v[188:191], v[42:45]
	v_mfma_f32_16x16x32_bf16 v[30:33], v[142:145], v[196:199], v[30:33]
	v_mfma_f32_16x16x32_bf16 v[26:29], v[156:159], v[196:199], v[26:29]
	v_mfma_f32_16x16x32_bf16 v[14:17], v[142:145], v[204:207], v[14:17]
	v_mfma_f32_16x16x32_bf16 v[10:13], v[156:159], v[204:207], v[10:13]
	v_mfma_f32_16x16x32_bf16 v[62:65], v[152:155], v[184:187], v[62:65]
	v_mfma_f32_16x16x32_bf16 v[58:61], v[160:163], v[184:187], v[58:61]
	v_mfma_f32_16x16x32_bf16 v[46:49], v[152:155], v[192:195], v[46:49]
	v_mfma_f32_16x16x32_bf16 v[42:45], v[160:163], v[192:195], v[42:45]
	v_mfma_f32_16x16x32_bf16 v[30:33], v[152:155], v[200:203], v[30:33]
	v_mfma_f32_16x16x32_bf16 v[26:29], v[160:163], v[200:203], v[26:29]
	v_mfma_f32_16x16x32_bf16 v[14:17], v[152:155], v[208:211], v[14:17]
	v_mfma_f32_16x16x32_bf16 v[10:13], v[160:163], v[208:211], v[10:13]
	v_mfma_f32_16x16x32_bf16 v[54:57], v[164:167], v[180:183], v[54:57]
	v_mfma_f32_16x16x32_bf16 v[50:53], v[172:175], v[180:183], v[50:53]
	v_mfma_f32_16x16x32_bf16 v[38:41], v[164:167], v[188:191], v[38:41]
	v_mfma_f32_16x16x32_bf16 v[34:37], v[172:175], v[188:191], v[34:37]
	v_mfma_f32_16x16x32_bf16 v[22:25], v[164:167], v[196:199], v[22:25]
	v_mfma_f32_16x16x32_bf16 v[18:21], v[172:175], v[196:199], v[18:21]
	v_mfma_f32_16x16x32_bf16 v[6:9], v[164:167], v[204:207], v[6:9]
	v_mfma_f32_16x16x32_bf16 v[2:5], v[172:175], v[204:207], v[2:5]
	v_mfma_f32_16x16x32_bf16 v[54:57], v[168:171], v[184:187], v[54:57]
	v_mfma_f32_16x16x32_bf16 v[50:53], v[176:179], v[184:187], v[50:53]
	v_mfma_f32_16x16x32_bf16 v[38:41], v[168:171], v[192:195], v[38:41]
	v_mfma_f32_16x16x32_bf16 v[34:37], v[176:179], v[192:195], v[34:37]
	v_mfma_f32_16x16x32_bf16 v[22:25], v[168:171], v[200:203], v[22:25]
	v_mfma_f32_16x16x32_bf16 v[18:21], v[176:179], v[200:203], v[18:21]
	v_mfma_f32_16x16x32_bf16 v[6:9], v[168:171], v[208:211], v[6:9]
	v_mfma_f32_16x16x32_bf16 v[2:5], v[176:179], v[208:211], v[2:5]
	s_barrier
	s_add_i32 s75, s75, 2
	s_add_u32 s48, s48, 0x100
	s_addc_u32 s49, s49, 0
	s_add_u32 s73, s73, 0x100
	s_addc_u32 s74, s74, 0
	s_cmp_gt_u32 s75, 13
	s_cbranch_scc0 .LBB0_866
	s_and_b64 vcc, exec, s[16:17]
	s_cbranch_vccz .LBB0_869
	s_barrier

; #define PG8_STAGE(bufoff, gbase, voff) do { _Pragma("unroll") for (int _i = 0; _i < 2; ++_i) \
;         __builtin_amdgcn_global_load_lds((const unsigned*)((const char*)(gbase) + (voff)[_i]), (PG8_LAS unsigned*)(lds + (bufoff) + ldsw + _i * 8192), 16, 0, 0); } while (0)
; #define PG8_LDA(dst, b, h) do { _Pragma("unroll") for (int m = 0; m < 4; ++m) _Pragma("unroll") for (int k = 0; k < 2; ++k) dst[m][k] = *(const PG8_LAS bf16x8*)(lds + PG8_SA(b, h) + aoff + m * 2048 + k * 1024); } while (0)
; #define PG8_LDB(dst, b, h) do { _Pragma("unroll") for (int n = 0; n < 2; ++n) _Pragma("unroll") for (int k = 0; k < 2; ++k) dst[n][k] = *(const PG8_LAS bf16x8*)(lds + PG8_SB(b, h) + boff + n * 2048 + k * 1024); } while (0)
; #define PG8_MMA(ai, bj, At, Bt) do { __builtin_amdgcn_s_setprio(1); _Pragma("unroll") for (int m = 0; m < 4; ++m) _Pragma("unroll") for (int n = 0; n < 2; ++n) _Pragma("unroll") for (int k = 0; k < 2; ++k) \
;         acc[ai][bj][m][n] = __builtin_amdgcn_mfma_f32_16x16x32_bf16(Bt[n][k], At[m][k], acc[ai][bj][m][n], 0, 0, 0); __builtin_amdgcn_s_setprio(0); } while (0)
; #define PG8_WAIT_V(n) asm volatile("s_waitcnt vmcnt(" #n ")" ::: "memory")
; #define PG8_WAIT_L(n) asm volatile("s_waitcnt lgkmcnt(" #n ")" ::: "memory")
; #define PG8_BAR __builtin_amdgcn_s_barrier()
; #define PG8_SCHED __builtin_amdgcn_sched_barrier(0)
; template <class Epi, class Sched, bool ALIGN_EPI = false, bool SP2 = false>
; __device__ __forceinline__ void gemm_phase(PG8_LAS unsigned char* lds, const Gemm g, const Sched& S, const Epi& E) {
;     ...
;             PG8_LDB(B0, 0, 0); PG8_LDB(B1, 0, 1); PG8_SCHED; PG8_LDA(At, 0, 0); PG8_STAGE(PG8_SA(1, 1), a1 + hstep, voffA);
;             PG8_WAIT_V(8); PG8_WAIT_L(0); PG8_BAR; PG8_MMA(0, 0, At, B0); PG8_MMA(0, 1, At, B1); PG8_BAR; PG8_SCHED;
;             PG8_LDA(At, 0, 1); PG8_STAGE(PG8_SB(0, 0), b2, voffB); PG8_STAGE(PG8_SB(0, 1), b2 + hstep, voffB); PG8_STAGE(PG8_SA(0, 0), a2, voffA);
;             PG8_WAIT_V(8); PG8_WAIT_L(0); PG8_BAR; PG8_MMA(1, 0, At, B0); PG8_MMA(1, 1, At, B1); PG8_BAR; PG8_SCHED;
.LBB0_1265:
	ds_read_b128 v[152:155], v140
	ds_read_b128 v[156:159], v140 offset:1024
	ds_read_b128 v[160:163], v140 offset:2048
	ds_read_b128 v[164:167], v140 offset:3072
	ds_read_b128 v[168:171], v141
	ds_read_b128 v[172:175], v141 offset:1024
	ds_read_b128 v[176:179], v141 offset:2048
	ds_read_b128 v[180:183], v141 offset:3072
	s_add_u32 s16, s12, s14
	s_addc_u32 s17, s13, s15
	s_add_u32 s16, s16, 0xb946100
	s_addc_u32 s17, s17, 0
	s_add_u32 s54, s39, s14
	s_addc_u32 s55, s40, s15
	s_cmpk_eq_i32 s14, 0x700
	s_cselect_b32 s19, s7, s17
	s_cselect_b32 s18, s6, s16
	s_cselect_b32 s17, s1, s55
	s_cselect_b32 s16, s0, s54
	s_mov_b32 m0, s44
	v_lshl_add_u64 v[216:217], v[136:137], 0, s[14:15]
	ds_read_b128 v[184:187], v142
	ds_read_b128 v[188:191], v142 offset:1024
	ds_read_b128 v[192:195], v142 offset:2048
	ds_read_b128 v[196:199], v142 offset:3072
	ds_read_b128 v[200:203], v142 offset:4096
	ds_read_b128 v[204:207], v142 offset:5120
	ds_read_b128 v[208:211], v142 offset:6144
	ds_read_b128 v[212:215], v142 offset:7168
	global_load_lds_dwordx4 v[216:217], off
	v_lshl_add_u64 v[216:217], v[138:139], 0, s[14:15]
	s_mov_b32 m0, s45
	s_nop 0
	global_load_lds_dwordx4 v[216:217], off
	s_waitcnt vmcnt(8)
	s_waitcnt lgkmcnt(0)
	s_barrier
	s_waitcnt lgkmcnt(0)
	v_mfma_f32_16x16x32_bf16 v[126:129], v[152:155], v[184:187], v[126:129]
	v_mfma_f32_16x16x32_bf16 v[122:125], v[160:163], v[184:187], v[122:125]
	v_mfma_f32_16x16x32_bf16 v[110:113], v[152:155], v[192:195], v[110:113]
	v_mfma_f32_16x16x32_bf16 v[106:109], v[160:163], v[192:195], v[106:109]
	v_mfma_f32_16x16x32_bf16 v[94:97], v[152:155], v[200:203], v[94:97]
	v_mfma_f32_16x16x32_bf16 v[90:93], v[160:163], v[200:203], v[90:93]
	v_mfma_f32_16x16x32_bf16 v[78:81], v[152:155], v[208:211], v[78:81]
	v_mfma_f32_16x16x32_bf16 v[74:77], v[160:163], v[208:211], v[74:77]
	v_mfma_f32_16x16x32_bf16 v[126:129], v[156:159], v[188:191], v[126:129]
	v_mfma_f32_16x16x32_bf16 v[122:125], v[164:167], v[188:191], v[122:125]
	v_mfma_f32_16x16x32_bf16 v[110:113], v[156:159], v[196:199], v[110:113]
	v_mfma_f32_16x16x32_bf16 v[106:109], v[164:167], v[196:199], v[106:109]
	v_mfma_f32_16x16x32_bf16 v[94:97], v[156:159], v[204:207], v[94:97]
	v_mfma_f32_16x16x32_bf16 v[90:93], v[164:167], v[204:207], v[90:93]
	v_mfma_f32_16x16x32_bf16 v[78:81], v[156:159], v[212:215], v[78:81]
	v_mfma_f32_16x16x32_bf16 v[74:77], v[164:167], v[212:215], v[74:77]
	v_mfma_f32_16x16x32_bf16 v[118:121], v[168:171], v[184:187], v[118:121]
	v_mfma_f32_16x16x32_bf16 v[114:117], v[176:179], v[184:187], v[114:117]
	v_mfma_f32_16x16x32_bf16 v[102:105], v[168:171], v[192:195], v[102:105]
	v_mfma_f32_16x16x32_bf16 v[98:101], v[176:179], v[192:195], v[98:101]
	v_mfma_f32_16x16x32_bf16 v[86:89], v[168:171], v[200:203], v[86:89]
	v_mfma_f32_16x16x32_bf16 v[82:85], v[176:179], v[200:203], v[82:85]
	v_mfma_f32_16x16x32_bf16 v[70:73], v[168:171], v[208:211], v[70:73]
	v_mfma_f32_16x16x32_bf16 v[66:69], v[176:179], v[208:211], v[66:69]
	v_mfma_f32_16x16x32_bf16 v[118:121], v[172:175], v[188:191], v[118:121]
	v_mfma_f32_16x16x32_bf16 v[114:117], v[180:183], v[188:191], v[114:117]
	v_mfma_f32_16x16x32_bf16 v[102:105], v[172:175], v[196:199], v[102:105]
	v_mfma_f32_16x16x32_bf16 v[98:101], v[180:183], v[196:199], v[98:101]
	v_mfma_f32_16x16x32_bf16 v[86:89], v[172:175], v[204:207], v[86:89]
	v_mfma_f32_16x16x32_bf16 v[82:85], v[180:183], v[204:207], v[82:85]
	v_mfma_f32_16x16x32_bf16 v[70:73], v[172:175], v[212:215], v[70:73]
	v_mfma_f32_16x16x32_bf16 v[66:69], v[180:183], v[212:215], v[66:69]
	s_barrier
	s_mov_b32 m0, s46
	v_lshl_add_u64 v[216:217], s[16:17], 0, v[130:131]
	s_add_u32 s54, s16, 0x40000
	ds_read_b128 v[184:187], v142 offset:16384
	ds_read_b128 v[188:191], v142 offset:17408
	ds_read_b128 v[192:195], v142 offset:18432
	ds_read_b128 v[196:199], v142 offset:19456
	ds_read_b128 v[200:203], v142 offset:20480
	ds_read_b128 v[204:207], v142 offset:21504
	ds_read_b128 v[208:211], v142 offset:22528
	ds_read_b128 v[212:215], v142 offset:23552
	global_load_lds_dwordx4 v[216:217], off
	v_lshl_add_u64 v[218:219], s[16:17], 0, v[132:133]
	s_mov_b32 m0, s47
	s_addc_u32 s55, s17, 0
	global_load_lds_dwordx4 v[218:219], off
	v_lshl_add_u64 v[220:221], s[54:55], 0, v[130:131]
	s_mov_b32 m0, s48
	v_lshl_add_u64 v[222:223], s[18:19], 0, v[132:133]
	global_load_lds_dwordx4 v[220:221], off
	v_lshl_add_u64 v[220:221], s[54:55], 0, v[132:133]
	s_mov_b32 m0, s49
	s_nop 0
	global_load_lds_dwordx4 v[220:221], off
	v_lshl_add_u64 v[220:221], s[18:19], 0, v[130:131]
	s_mov_b32 m0, s30
	s_nop 0
	global_load_lds_dwordx4 v[220:221], off
	s_mov_b32 m0, s31
	s_nop 0
	global_load_lds_dwordx4 v[222:223], off
	s_waitcnt vmcnt(8)
	s_waitcnt lgkmcnt(0)
	s_barrier
; #define PG8_STAGE(bufoff, gbase, voff) do { _Pragma("unroll") for (int _i = 0; _i < 2; ++_i) \
;         __builtin_amdgcn_global_load_lds((const unsigned*)((const char*)(gbase) + (voff)[_i]), (PG8_LAS unsigned*)(lds + (bufoff) + ldsw + _i * 8192), 16, 0, 0); } while (0)
; #define PG8_LDA(dst, b, h) do { _Pragma("unroll") for (int m = 0; m < 4; ++m) _Pragma("unroll") for (int k = 0; k < 2; ++k) dst[m][k] = *(const PG8_LAS bf16x8*)(lds + PG8_SA(b, h) + aoff + m * 2048 + k * 1024); } while (0)
; #define PG8_LDB(dst, b, h) do { _Pragma("unroll") for (int n = 0; n < 2; ++n) _Pragma("unroll") for (int k = 0; k < 2; ++k) dst[n][k] = *(const PG8_LAS bf16x8*)(lds + PG8_SB(b, h) + boff + n * 2048 + k * 1024); } while (0)
; #define PG8_MMA(ai, bj, At, Bt) do { __builtin_amdgcn_s_setprio(1); _Pragma("unroll") for (int m = 0; m < 4; ++m) _Pragma("unroll") for (int n = 0; n < 2; ++n) _Pragma("unroll") for (int k = 0; k < 2; ++k) \
;         acc[ai][bj][m][n] = __builtin_amdgcn_mfma_f32_16x16x32_bf16(Bt[n][k], At[m][k], acc[ai][bj][m][n], 0, 0, 0); __builtin_amdgcn_s_setprio(0); } while (0)
; #define PG8_WAIT_V(n) asm volatile("s_waitcnt vmcnt(" #n ")" ::: "memory")
; #define PG8_WAIT_L(n) asm volatile("s_waitcnt lgkmcnt(" #n ")" ::: "memory")
; #define PG8_BAR __builtin_amdgcn_s_barrier()
; #define PG8_SCHED __builtin_amdgcn_sched_barrier(0)
; template <class Epi, class Sched, bool ALIGN_EPI = false, bool SP2 = false>
; __device__ __forceinline__ void gemm_phase(PG8_LAS unsigned char* lds, const Gemm g, const Sched& S, const Epi& E) {
;     ...
;             PG8_WAIT_V(8); PG8_WAIT_L(0); PG8_BAR; PG8_MMA(1, 0, At, B0); PG8_MMA(1, 1, At, B1); PG8_BAR; PG8_SCHED;
;             PG8_LDB(B0, 1, 0); PG8_LDB(B1, 1, 1); PG8_SCHED; PG8_LDA(At, 1, 0); PG8_STAGE(PG8_SA(0, 1), a2 + hstep, voffA);
;             PG8_WAIT_V(8); PG8_WAIT_L(0); PG8_BAR; PG8_MMA(0, 0, At, B0); PG8_MMA(0, 1, At, B1); PG8_BAR; PG8_SCHED;
	s_waitcnt lgkmcnt(0)
	v_mfma_f32_16x16x32_bf16 v[62:65], v[152:155], v[184:187], v[62:65]
	v_mfma_f32_16x16x32_bf16 v[58:61], v[160:163], v[184:187], v[58:61]
	v_mfma_f32_16x16x32_bf16 v[46:49], v[152:155], v[192:195], v[46:49]
	v_mfma_f32_16x16x32_bf16 v[42:45], v[160:163], v[192:195], v[42:45]
	v_mfma_f32_16x16x32_bf16 v[30:33], v[152:155], v[200:203], v[30:33]
	v_mfma_f32_16x16x32_bf16 v[26:29], v[160:163], v[200:203], v[26:29]
	v_mfma_f32_16x16x32_bf16 v[14:17], v[152:155], v[208:211], v[14:17]
	v_mfma_f32_16x16x32_bf16 v[10:13], v[160:163], v[208:211], v[10:13]
	v_mfma_f32_16x16x32_bf16 v[62:65], v[156:159], v[188:191], v[62:65]
	v_mfma_f32_16x16x32_bf16 v[58:61], v[164:167], v[188:191], v[58:61]
	v_mfma_f32_16x16x32_bf16 v[46:49], v[156:159], v[196:199], v[46:49]
	v_mfma_f32_16x16x32_bf16 v[42:45], v[164:167], v[196:199], v[42:45]
	v_mfma_f32_16x16x32_bf16 v[30:33], v[156:159], v[204:207], v[30:33]
	v_mfma_f32_16x16x32_bf16 v[26:29], v[164:167], v[204:207], v[26:29]
	v_mfma_f32_16x16x32_bf16 v[14:17], v[156:159], v[212:215], v[14:17]
	v_mfma_f32_16x16x32_bf16 v[10:13], v[164:167], v[212:215], v[10:13]
	v_mfma_f32_16x16x32_bf16 v[54:57], v[168:171], v[184:187], v[54:57]
	v_mfma_f32_16x16x32_bf16 v[50:53], v[176:179], v[184:187], v[50:53]
	v_mfma_f32_16x16x32_bf16 v[38:41], v[168:171], v[192:195], v[38:41]
	v_mfma_f32_16x16x32_bf16 v[34:37], v[176:179], v[192:195], v[34:37]
	v_mfma_f32_16x16x32_bf16 v[22:25], v[168:171], v[200:203], v[22:25]
	v_mfma_f32_16x16x32_bf16 v[18:21], v[176:179], v[200:203], v[18:21]
	v_mfma_f32_16x16x32_bf16 v[6:9], v[168:171], v[208:211], v[6:9]
	v_mfma_f32_16x16x32_bf16 v[2:5], v[176:179], v[208:211], v[2:5]
	v_mfma_f32_16x16x32_bf16 v[54:57], v[172:175], v[188:191], v[54:57]
	v_mfma_f32_16x16x32_bf16 v[50:53], v[180:183], v[188:191], v[50:53]
	v_mfma_f32_16x16x32_bf16 v[38:41], v[172:175], v[196:199], v[38:41]
	v_mfma_f32_16x16x32_bf16 v[34:37], v[180:183], v[196:199], v[34:37]
	v_mfma_f32_16x16x32_bf16 v[22:25], v[172:175], v[204:207], v[22:25]
	v_mfma_f32_16x16x32_bf16 v[18:21], v[180:183], v[204:207], v[18:21]
	v_mfma_f32_16x16x32_bf16 v[6:9], v[172:175], v[212:215], v[6:9]
	v_mfma_f32_16x16x32_bf16 v[2:5], v[180:183], v[212:215], v[2:5]
	s_barrier
	ds_read_b128 v[152:155], v143
	ds_read_b128 v[156:159], v143 offset:1024
	ds_read_b128 v[160:163], v143 offset:2048
	ds_read_b128 v[164:167], v143 offset:3072
	ds_read_b128 v[168:171], v151
	ds_read_b128 v[172:175], v151 offset:1024
	ds_read_b128 v[176:179], v151 offset:2048
	ds_read_b128 v[180:183], v151 offset:3072
	s_add_u32 s18, s18, 0x40000
	s_addc_u32 s19, s19, 0
	s_mov_b32 m0, s34
	v_lshl_add_u64 v[224:225], s[18:19], 0, v[130:131]
	ds_read_b128 v[184:187], v142 offset:32768
	ds_read_b128 v[188:191], v142 offset:33792
	ds_read_b128 v[192:195], v142 offset:34816
	ds_read_b128 v[196:199], v142 offset:35840
	ds_read_b128 v[200:203], v142 offset:36864
	ds_read_b128 v[204:207], v142 offset:37888
	ds_read_b128 v[208:211], v142 offset:38912
	ds_read_b128 v[212:215], v142 offset:39936
	global_load_lds_dwordx4 v[224:225], off
	v_lshl_add_u64 v[224:225], s[18:19], 0, v[132:133]
	s_mov_b32 m0, s36
	s_nop 0
	global_load_lds_dwordx4 v[224:225], off
	s_waitcnt vmcnt(8)
	s_waitcnt lgkmcnt(0)
	s_barrier
	s_waitcnt lgkmcnt(0)
	v_mfma_f32_16x16x32_bf16 v[126:129], v[152:155], v[184:187], v[126:129]
	v_mfma_f32_16x16x32_bf16 v[122:125], v[160:163], v[184:187], v[122:125]
	v_mfma_f32_16x16x32_bf16 v[110:113], v[152:155], v[192:195], v[110:113]
	v_mfma_f32_16x16x32_bf16 v[106:109], v[160:163], v[192:195], v[106:109]
	v_mfma_f32_16x16x32_bf16 v[94:97], v[152:155], v[200:203], v[94:97]
	v_mfma_f32_16x16x32_bf16 v[90:93], v[160:163], v[200:203], v[90:93]
	v_mfma_f32_16x16x32_bf16 v[78:81], v[152:155], v[208:211], v[78:81]
	v_mfma_f32_16x16x32_bf16 v[74:77], v[160:163], v[208:211], v[74:77]
	v_mfma_f32_16x16x32_bf16 v[126:129], v[156:159], v[188:191], v[126:129]
	v_mfma_f32_16x16x32_bf16 v[122:125], v[164:167], v[188:191], v[122:125]
	v_mfma_f32_16x16x32_bf16 v[110:113], v[156:159], v[196:199], v[110:113]
	v_mfma_f32_16x16x32_bf16 v[106:109], v[164:167], v[196:199], v[106:109]
	v_mfma_f32_16x16x32_bf16 v[94:97], v[156:159], v[204:207], v[94:97]
	v_mfma_f32_16x16x32_bf16 v[90:93], v[164:167], v[204:207], v[90:93]
	v_mfma_f32_16x16x32_bf16 v[78:81], v[156:159], v[212:215], v[78:81]
	v_mfma_f32_16x16x32_bf16 v[74:77], v[164:167], v[212:215], v[74:77]
	v_mfma_f32_16x16x32_bf16 v[118:121], v[168:171], v[184:187], v[118:121]
	v_mfma_f32_16x16x32_bf16 v[114:117], v[176:179], v[184:187], v[114:117]
	v_mfma_f32_16x16x32_bf16 v[102:105], v[168:171], v[192:195], v[102:105]
	v_mfma_f32_16x16x32_bf16 v[98:101], v[176:179], v[192:195], v[98:101]
	v_mfma_f32_16x16x32_bf16 v[86:89], v[168:171], v[200:203], v[86:89]
	v_mfma_f32_16x16x32_bf16 v[82:85], v[176:179], v[200:203], v[82:85]
	v_mfma_f32_16x16x32_bf16 v[70:73], v[168:171], v[208:211], v[70:73]
	v_mfma_f32_16x16x32_bf16 v[66:69], v[176:179], v[208:211], v[66:69]
	v_mfma_f32_16x16x32_bf16 v[118:121], v[172:175], v[188:191], v[118:121]
	v_mfma_f32_16x16x32_bf16 v[114:117], v[180:183], v[188:191], v[114:117]
	v_mfma_f32_16x16x32_bf16 v[102:105], v[172:175], v[196:199], v[102:105]
	v_mfma_f32_16x16x32_bf16 v[98:101], v[180:183], v[196:199], v[98:101]
	v_mfma_f32_16x16x32_bf16 v[86:89], v[172:175], v[204:207], v[86:89]
	v_mfma_f32_16x16x32_bf16 v[82:85], v[180:183], v[204:207], v[82:85]
	v_mfma_f32_16x16x32_bf16 v[70:73], v[172:175], v[212:215], v[70:73]
	v_mfma_f32_16x16x32_bf16 v[66:69], v[180:183], v[212:215], v[66:69]
	s_barrier
; #define PG8_STAGE(bufoff, gbase, voff) do { _Pragma("unroll") for (int _i = 0; _i < 2; ++_i) \
;         __builtin_amdgcn_global_load_lds((const unsigned*)((const char*)(gbase) + (voff)[_i]), (PG8_LAS unsigned*)(lds + (bufoff) + ldsw + _i * 8192), 16, 0, 0); } while (0)
; #define PG8_LDA(dst, b, h) do { _Pragma("unroll") for (int m = 0; m < 4; ++m) _Pragma("unroll") for (int k = 0; k < 2; ++k) dst[m][k] = *(const PG8_LAS bf16x8*)(lds + PG8_SA(b, h) + aoff + m * 2048 + k * 1024); } while (0)
; #define PG8_MMA(ai, bj, At, Bt) do { __builtin_amdgcn_s_setprio(1); _Pragma("unroll") for (int m = 0; m < 4; ++m) _Pragma("unroll") for (int n = 0; n < 2; ++n) _Pragma("unroll") for (int k = 0; k < 2; ++k) \
;         acc[ai][bj][m][n] = __builtin_amdgcn_mfma_f32_16x16x32_bf16(Bt[n][k], At[m][k], acc[ai][bj][m][n], 0, 0, 0); __builtin_amdgcn_s_setprio(0); } while (0)
; #define PG8_WAIT_V(n) asm volatile("s_waitcnt vmcnt(" #n ")" ::: "memory")
; #define PG8_WAIT_L(n) asm volatile("s_waitcnt lgkmcnt(" #n ")" ::: "memory")
; #define PG8_BAR __builtin_amdgcn_s_barrier()
; #define PG8_SCHED __builtin_amdgcn_sched_barrier(0)
; template <class Epi, class Sched, bool ALIGN_EPI = false, bool SP2 = false>
; __device__ __forceinline__ void gemm_phase(PG8_LAS unsigned char* lds, const Gemm g, const Sched& S, const Epi& E) {
;     ...
;         for (int t = 0; t < nt; t += 2) {
;             const bool last = (t == nt - 2);
;             const char* a1 = cA + (size_t)(t + 1) * kstep;
;             const char* a2 = last ? nA : cA + (size_t)(t + 2) * kstep; const char* b2 = last ? nB : cB + (size_t)(t + 2) * kstep;
;     ...
;             PG8_LDA(At, 1, 1); PG8_STAGE(PG8_SB(1, 0), b3, voffB); PG8_STAGE(PG8_SB(1, 1), b3 + hstep, voffB); PG8_STAGE(PG8_SA(1, 0), a3, voffA);
;             PG8_WAIT_V(8); PG8_WAIT_L(0); PG8_BAR; PG8_MMA(1, 0, At, B0); PG8_MMA(1, 1, At, B1); PG8_BAR; PG8_SCHED;
	s_mov_b32 m0, s50
	v_lshl_add_u64 v[216:217], v[216:217], 0, s[10:11]
	s_add_u32 s16, s16, 0x40080
	ds_read_b128 v[184:187], v142 offset:49152
	ds_read_b128 v[188:191], v142 offset:50176
	ds_read_b128 v[192:195], v142 offset:51200
	ds_read_b128 v[196:199], v142 offset:52224
	ds_read_b128 v[200:203], v142 offset:53248
	ds_read_b128 v[204:207], v142 offset:54272
	ds_read_b128 v[208:211], v142 offset:55296
	ds_read_b128 v[212:215], v142 offset:56320
	global_load_lds_dwordx4 v[216:217], off
	v_lshl_add_u64 v[216:217], v[218:219], 0, s[10:11]
	s_mov_b32 m0, s51
	s_addc_u32 s17, s17, 0
	global_load_lds_dwordx4 v[216:217], off
	v_lshl_add_u64 v[216:217], s[16:17], 0, v[130:131]
	s_mov_b32 m0, s52
	s_nop 0
	global_load_lds_dwordx4 v[216:217], off
	v_lshl_add_u64 v[216:217], s[16:17], 0, v[132:133]
	s_mov_b32 m0, s53
	s_nop 0
	global_load_lds_dwordx4 v[216:217], off
	v_lshl_add_u64 v[216:217], v[220:221], 0, s[10:11]
	s_mov_b32 m0, s37
	s_nop 0
	global_load_lds_dwordx4 v[216:217], off
	v_lshl_add_u64 v[216:217], v[222:223], 0, s[10:11]
	s_mov_b32 m0, s38
	s_nop 0
	global_load_lds_dwordx4 v[216:217], off
	s_waitcnt vmcnt(8)
	s_waitcnt lgkmcnt(0)
	s_barrier
	s_waitcnt lgkmcnt(0)
	v_mfma_f32_16x16x32_bf16 v[62:65], v[152:155], v[184:187], v[62:65]
	v_mfma_f32_16x16x32_bf16 v[58:61], v[160:163], v[184:187], v[58:61]
	v_mfma_f32_16x16x32_bf16 v[46:49], v[152:155], v[192:195], v[46:49]
	v_mfma_f32_16x16x32_bf16 v[42:45], v[160:163], v[192:195], v[42:45]
	v_mfma_f32_16x16x32_bf16 v[30:33], v[152:155], v[200:203], v[30:33]
	v_mfma_f32_16x16x32_bf16 v[26:29], v[160:163], v[200:203], v[26:29]
	v_mfma_f32_16x16x32_bf16 v[14:17], v[152:155], v[208:211], v[14:17]
	v_mfma_f32_16x16x32_bf16 v[10:13], v[160:163], v[208:211], v[10:13]
	v_mfma_f32_16x16x32_bf16 v[62:65], v[156:159], v[188:191], v[62:65]
	v_mfma_f32_16x16x32_bf16 v[58:61], v[164:167], v[188:191], v[58:61]
	v_mfma_f32_16x16x32_bf16 v[46:49], v[156:159], v[196:199], v[46:49]
	v_mfma_f32_16x16x32_bf16 v[42:45], v[164:167], v[196:199], v[42:45]
	v_mfma_f32_16x16x32_bf16 v[30:33], v[156:159], v[204:207], v[30:33]
	v_mfma_f32_16x16x32_bf16 v[26:29], v[164:167], v[204:207], v[26:29]
	v_mfma_f32_16x16x32_bf16 v[14:17], v[156:159], v[212:215], v[14:17]
	v_mfma_f32_16x16x32_bf16 v[10:13], v[164:167], v[212:215], v[10:13]
	v_mfma_f32_16x16x32_bf16 v[54:57], v[168:171], v[184:187], v[54:57]
	v_mfma_f32_16x16x32_bf16 v[50:53], v[176:179], v[184:187], v[50:53]
	v_mfma_f32_16x16x32_bf16 v[38:41], v[168:171], v[192:195], v[38:41]
	v_mfma_f32_16x16x32_bf16 v[34:37], v[176:179], v[192:195], v[34:37]
	v_mfma_f32_16x16x32_bf16 v[22:25], v[168:171], v[200:203], v[22:25]
	v_mfma_f32_16x16x32_bf16 v[18:21], v[176:179], v[200:203], v[18:21]
	v_mfma_f32_16x16x32_bf16 v[6:9], v[168:171], v[208:211], v[6:9]
	v_mfma_f32_16x16x32_bf16 v[2:5], v[176:179], v[208:211], v[2:5]
	v_mfma_f32_16x16x32_bf16 v[54:57], v[172:175], v[188:191], v[54:57]
	v_mfma_f32_16x16x32_bf16 v[50:53], v[180:183], v[188:191], v[50:53]
	v_mfma_f32_16x16x32_bf16 v[38:41], v[172:175], v[196:199], v[38:41]
	v_mfma_f32_16x16x32_bf16 v[34:37], v[180:183], v[196:199], v[34:37]
	v_mfma_f32_16x16x32_bf16 v[22:25], v[172:175], v[204:207], v[22:25]
	v_mfma_f32_16x16x32_bf16 v[18:21], v[180:183], v[204:207], v[18:21]
	v_mfma_f32_16x16x32_bf16 v[6:9], v[172:175], v[212:215], v[6:9]
	v_mfma_f32_16x16x32_bf16 v[2:5], v[180:183], v[212:215], v[2:5]
	s_barrier
	s_add_i32 s41, s41, 2
	s_add_u32 s14, s14, 0x100
	s_addc_u32 s15, s15, 0
	s_cmp_gt_u32 s41, 13
	s_cbranch_scc0 .LBB0_1265
	s_cmpk_lt_u32 s28, 0x100
	s_cbranch_scc0 .LBB0_1268
	s_barrier

; #define PG8_STAGE(bufoff, gbase, voff) do { _Pragma("unroll") for (int _i = 0; _i < 2; ++_i) \
;         __builtin_amdgcn_global_load_lds((const unsigned*)((const char*)(gbase) + (voff)[_i]), (PG8_LAS unsigned*)(lds + (bufoff) + ldsw + _i * 8192), 16, 0, 0); } while (0)
; #define PG8_LDA(dst, b, h) do { _Pragma("unroll") for (int m = 0; m < 4; ++m) _Pragma("unroll") for (int k = 0; k < 2; ++k) dst[m][k] = *(const PG8_LAS bf16x8*)(lds + PG8_SA(b, h) + aoff + m * 2048 + k * 1024); } while (0)
; #define PG8_LDB(dst, b, h) do { _Pragma("unroll") for (int n = 0; n < 2; ++n) _Pragma("unroll") for (int k = 0; k < 2; ++k) dst[n][k] = *(const PG8_LAS bf16x8*)(lds + PG8_SB(b, h) + boff + n * 2048 + k * 1024); } while (0)
; #define PG8_MMA(ai, bj, At, Bt) do { __builtin_amdgcn_s_setprio(1); _Pragma("unroll") for (int m = 0; m < 4; ++m) _Pragma("unroll") for (int n = 0; n < 2; ++n) _Pragma("unroll") for (int k = 0; k < 2; ++k) \
;         acc[ai][bj][m][n] = __builtin_amdgcn_mfma_f32_16x16x32_bf16(Bt[n][k], At[m][k], acc[ai][bj][m][n], 0, 0, 0); __builtin_amdgcn_s_setprio(0); } while (0)
; #define PG8_WAIT_V(n) asm volatile("s_waitcnt vmcnt(" #n ")" ::: "memory")
; #define PG8_WAIT_L(n) asm volatile("s_waitcnt lgkmcnt(" #n ")" ::: "memory")
; #define PG8_BAR __builtin_amdgcn_s_barrier()
; #define PG8_SCHED __builtin_amdgcn_sched_barrier(0)
; template <class Epi, class Sched, bool ALIGN_EPI = false, bool SP2 = false>
; __device__ __forceinline__ void gemm_phase(PG8_LAS unsigned char* lds, const Gemm g, const Sched& S, const Epi& E) {
;     ...
;             PG8_LDB(B0, 0, 0); PG8_LDB(B1, 0, 1); PG8_SCHED; PG8_LDA(At, 0, 0); PG8_STAGE(PG8_SA(1, 1), a1 + hstep, voffA);
;             PG8_WAIT_V(8); PG8_WAIT_L(0); PG8_BAR; PG8_MMA(0, 0, At, B0); PG8_MMA(0, 1, At, B1); PG8_BAR; PG8_SCHED;
;             PG8_LDA(At, 0, 1); PG8_STAGE(PG8_SB(0, 0), b2, voffB); PG8_STAGE(PG8_SB(0, 1), b2 + hstep, voffB); PG8_STAGE(PG8_SA(0, 0), a2, voffA);
;             PG8_WAIT_V(8); PG8_WAIT_L(0); PG8_BAR; PG8_MMA(1, 0, At, B0); PG8_MMA(1, 1, At, B1); PG8_BAR; PG8_SCHED;
.LBB0_1309:
	ds_read_b128 v[146:149], v1
	ds_read_b128 v[150:153], v1 offset:1024
	ds_read_b128 v[154:157], v1 offset:2048
	ds_read_b128 v[158:161], v1 offset:3072
	ds_read_b128 v[162:165], v143
	ds_read_b128 v[166:169], v143 offset:1024
	ds_read_b128 v[170:173], v143 offset:2048
	ds_read_b128 v[174:177], v143 offset:3072
	s_add_u32 s38, s36, 0xfffc0080
	s_addc_u32 s39, s37, -1
	s_cmp_eq_u32 s65, 12
	s_cselect_b32 s41, s7, s39
	s_cselect_b32 s40, s61, s38
	s_cselect_b32 s39, s19, s64
	s_cselect_b32 s38, s62, s63
	v_lshl_add_u64 v[138:139], s[36:37], 0, v[134:135]
	s_add_i32 m0, s49, 0xc000
	ds_read_b128 v[178:181], v144
	ds_read_b128 v[182:185], v144 offset:1024
	ds_read_b128 v[186:189], v144 offset:2048
	ds_read_b128 v[190:193], v144 offset:3072
	ds_read_b128 v[194:197], v144 offset:4096
	ds_read_b128 v[198:201], v144 offset:5120
	ds_read_b128 v[202:205], v144 offset:6144
	ds_read_b128 v[206:209], v144 offset:7168
	global_load_lds_dwordx4 v[138:139], off
	v_lshl_add_u64 v[138:139], s[36:37], 0, v[136:137]
	s_add_i32 m0, s49, 0xe000
	s_nop 0
	global_load_lds_dwordx4 v[138:139], off
	s_waitcnt vmcnt(8)
	s_waitcnt lgkmcnt(0)
	s_barrier
	s_waitcnt lgkmcnt(0)
	v_mfma_f32_16x16x32_bf16 v[126:129], v[146:149], v[178:181], v[126:129]
	v_mfma_f32_16x16x32_bf16 v[122:125], v[154:157], v[178:181], v[122:125]
	v_mfma_f32_16x16x32_bf16 v[110:113], v[146:149], v[186:189], v[110:113]
	v_mfma_f32_16x16x32_bf16 v[106:109], v[154:157], v[186:189], v[106:109]
	v_mfma_f32_16x16x32_bf16 v[94:97], v[146:149], v[194:197], v[94:97]
	v_mfma_f32_16x16x32_bf16 v[90:93], v[154:157], v[194:197], v[90:93]
	v_mfma_f32_16x16x32_bf16 v[78:81], v[146:149], v[202:205], v[78:81]
	v_mfma_f32_16x16x32_bf16 v[74:77], v[154:157], v[202:205], v[74:77]
	v_mfma_f32_16x16x32_bf16 v[126:129], v[150:153], v[182:185], v[126:129]
	v_mfma_f32_16x16x32_bf16 v[122:125], v[158:161], v[182:185], v[122:125]
	v_mfma_f32_16x16x32_bf16 v[110:113], v[150:153], v[190:193], v[110:113]
	v_mfma_f32_16x16x32_bf16 v[106:109], v[158:161], v[190:193], v[106:109]
	v_mfma_f32_16x16x32_bf16 v[94:97], v[150:153], v[198:201], v[94:97]
	v_mfma_f32_16x16x32_bf16 v[90:93], v[158:161], v[198:201], v[90:93]
	v_mfma_f32_16x16x32_bf16 v[78:81], v[150:153], v[206:209], v[78:81]
	v_mfma_f32_16x16x32_bf16 v[74:77], v[158:161], v[206:209], v[74:77]
	v_mfma_f32_16x16x32_bf16 v[118:121], v[162:165], v[178:181], v[118:121]
	v_mfma_f32_16x16x32_bf16 v[114:117], v[170:173], v[178:181], v[114:117]
	v_mfma_f32_16x16x32_bf16 v[102:105], v[162:165], v[186:189], v[102:105]
	v_mfma_f32_16x16x32_bf16 v[98:101], v[170:173], v[186:189], v[98:101]
	v_mfma_f32_16x16x32_bf16 v[86:89], v[162:165], v[194:197], v[86:89]
	v_mfma_f32_16x16x32_bf16 v[82:85], v[170:173], v[194:197], v[82:85]
	v_mfma_f32_16x16x32_bf16 v[70:73], v[162:165], v[202:205], v[70:73]
	v_mfma_f32_16x16x32_bf16 v[66:69], v[170:173], v[202:205], v[66:69]
	v_mfma_f32_16x16x32_bf16 v[118:121], v[166:169], v[182:185], v[118:121]
	v_mfma_f32_16x16x32_bf16 v[114:117], v[174:177], v[182:185], v[114:117]
	v_mfma_f32_16x16x32_bf16 v[102:105], v[166:169], v[190:193], v[102:105]
	v_mfma_f32_16x16x32_bf16 v[98:101], v[174:177], v[190:193], v[98:101]
	v_mfma_f32_16x16x32_bf16 v[86:89], v[166:169], v[198:201], v[86:89]
	v_mfma_f32_16x16x32_bf16 v[82:85], v[174:177], v[198:201], v[82:85]
	v_mfma_f32_16x16x32_bf16 v[70:73], v[166:169], v[206:209], v[70:73]
	v_mfma_f32_16x16x32_bf16 v[66:69], v[174:177], v[206:209], v[66:69]
	s_barrier
	s_add_i32 s66, s56, s48
	v_lshl_add_u64 v[138:139], s[38:39], 0, v[130:131]
	s_mov_b32 m0, s66
	ds_read_b128 v[178:181], v144 offset:16384
	ds_read_b128 v[182:185], v144 offset:17408
	ds_read_b128 v[186:189], v144 offset:18432
	ds_read_b128 v[190:193], v144 offset:19456
	ds_read_b128 v[194:197], v144 offset:20480
	ds_read_b128 v[198:201], v144 offset:21504
	ds_read_b128 v[202:205], v144 offset:22528
	ds_read_b128 v[206:209], v144 offset:23552
	global_load_lds_dwordx4 v[138:139], off
	s_add_i32 m0, s66, 0x2000
	s_add_u32 s66, s38, 0x40000
	v_lshl_add_u64 v[210:211], s[38:39], 0, v[132:133]
	s_addc_u32 s67, s39, 0
	s_add_i32 s68, s57, s48
	global_load_lds_dwordx4 v[210:211], off
	v_lshl_add_u64 v[212:213], s[66:67], 0, v[130:131]
	s_mov_b32 m0, s68
	v_lshl_add_u64 v[214:215], s[40:41], 0, v[132:133]
	global_load_lds_dwordx4 v[212:213], off
	v_lshl_add_u64 v[212:213], s[66:67], 0, v[132:133]
	s_add_i32 m0, s68, 0x2000
	s_nop 0
	global_load_lds_dwordx4 v[212:213], off
	v_lshl_add_u64 v[212:213], s[40:41], 0, v[130:131]
	s_mov_b32 m0, s49
	s_nop 0
	global_load_lds_dwordx4 v[212:213], off
	s_mov_b32 m0, s50
	s_nop 0
	global_load_lds_dwordx4 v[214:215], off
	s_waitcnt vmcnt(8)
	s_waitcnt lgkmcnt(0)
	s_barrier
; #define PG8_STAGE(bufoff, gbase, voff) do { _Pragma("unroll") for (int _i = 0; _i < 2; ++_i) \
;         __builtin_amdgcn_global_load_lds((const unsigned*)((const char*)(gbase) + (voff)[_i]), (PG8_LAS unsigned*)(lds + (bufoff) + ldsw + _i * 8192), 16, 0, 0); } while (0)
; #define PG8_LDA(dst, b, h) do { _Pragma("unroll") for (int m = 0; m < 4; ++m) _Pragma("unroll") for (int k = 0; k < 2; ++k) dst[m][k] = *(const PG8_LAS bf16x8*)(lds + PG8_SA(b, h) + aoff + m * 2048 + k * 1024); } while (0)
; #define PG8_LDB(dst, b, h) do { _Pragma("unroll") for (int n = 0; n < 2; ++n) _Pragma("unroll") for (int k = 0; k < 2; ++k) dst[n][k] = *(const PG8_LAS bf16x8*)(lds + PG8_SB(b, h) + boff + n * 2048 + k * 1024); } while (0)
; #define PG8_MMA(ai, bj, At, Bt) do { __builtin_amdgcn_s_setprio(1); _Pragma("unroll") for (int m = 0; m < 4; ++m) _Pragma("unroll") for (int n = 0; n < 2; ++n) _Pragma("unroll") for (int k = 0; k < 2; ++k) \
;         acc[ai][bj][m][n] = __builtin_amdgcn_mfma_f32_16x16x32_bf16(Bt[n][k], At[m][k], acc[ai][bj][m][n], 0, 0, 0); __builtin_amdgcn_s_setprio(0); } while (0)
; #define PG8_WAIT_V(n) asm volatile("s_waitcnt vmcnt(" #n ")" ::: "memory")
; #define PG8_WAIT_L(n) asm volatile("s_waitcnt lgkmcnt(" #n ")" ::: "memory")
; #define PG8_BAR __builtin_amdgcn_s_barrier()
; #define PG8_SCHED __builtin_amdgcn_sched_barrier(0)
; template <class Epi, class Sched, bool ALIGN_EPI = false, bool SP2 = false>
; __device__ __forceinline__ void gemm_phase(PG8_LAS unsigned char* lds, const Gemm g, const Sched& S, const Epi& E) {
;     ...
;             PG8_WAIT_V(8); PG8_WAIT_L(0); PG8_BAR; PG8_MMA(1, 0, At, B0); PG8_MMA(1, 1, At, B1); PG8_BAR; PG8_SCHED;
;             PG8_LDB(B0, 1, 0); PG8_LDB(B1, 1, 1); PG8_SCHED; PG8_LDA(At, 1, 0); PG8_STAGE(PG8_SA(0, 1), a2 + hstep, voffA);
;             PG8_WAIT_V(8); PG8_WAIT_L(0); PG8_BAR; PG8_MMA(0, 0, At, B0); PG8_MMA(0, 1, At, B1); PG8_BAR; PG8_SCHED;
	s_waitcnt lgkmcnt(0)
	v_mfma_f32_16x16x32_bf16 v[62:65], v[146:149], v[178:181], v[62:65]
	v_mfma_f32_16x16x32_bf16 v[58:61], v[154:157], v[178:181], v[58:61]
	v_mfma_f32_16x16x32_bf16 v[46:49], v[146:149], v[186:189], v[46:49]
	v_mfma_f32_16x16x32_bf16 v[42:45], v[154:157], v[186:189], v[42:45]
	v_mfma_f32_16x16x32_bf16 v[30:33], v[146:149], v[194:197], v[30:33]
	v_mfma_f32_16x16x32_bf16 v[26:29], v[154:157], v[194:197], v[26:29]
	v_mfma_f32_16x16x32_bf16 v[14:17], v[146:149], v[202:205], v[14:17]
	v_mfma_f32_16x16x32_bf16 v[10:13], v[154:157], v[202:205], v[10:13]
	v_mfma_f32_16x16x32_bf16 v[62:65], v[150:153], v[182:185], v[62:65]
	v_mfma_f32_16x16x32_bf16 v[58:61], v[158:161], v[182:185], v[58:61]
	v_mfma_f32_16x16x32_bf16 v[46:49], v[150:153], v[190:193], v[46:49]
	v_mfma_f32_16x16x32_bf16 v[42:45], v[158:161], v[190:193], v[42:45]
	v_mfma_f32_16x16x32_bf16 v[30:33], v[150:153], v[198:201], v[30:33]
	v_mfma_f32_16x16x32_bf16 v[26:29], v[158:161], v[198:201], v[26:29]
	v_mfma_f32_16x16x32_bf16 v[14:17], v[150:153], v[206:209], v[14:17]
	v_mfma_f32_16x16x32_bf16 v[10:13], v[158:161], v[206:209], v[10:13]
	v_mfma_f32_16x16x32_bf16 v[54:57], v[162:165], v[178:181], v[54:57]
	v_mfma_f32_16x16x32_bf16 v[50:53], v[170:173], v[178:181], v[50:53]
	v_mfma_f32_16x16x32_bf16 v[38:41], v[162:165], v[186:189], v[38:41]
	v_mfma_f32_16x16x32_bf16 v[34:37], v[170:173], v[186:189], v[34:37]
	v_mfma_f32_16x16x32_bf16 v[22:25], v[162:165], v[194:197], v[22:25]
	v_mfma_f32_16x16x32_bf16 v[18:21], v[170:173], v[194:197], v[18:21]
	v_mfma_f32_16x16x32_bf16 v[6:9], v[162:165], v[202:205], v[6:9]
	v_mfma_f32_16x16x32_bf16 v[2:5], v[170:173], v[202:205], v[2:5]
	v_mfma_f32_16x16x32_bf16 v[54:57], v[166:169], v[182:185], v[54:57]
	v_mfma_f32_16x16x32_bf16 v[50:53], v[174:177], v[182:185], v[50:53]
	v_mfma_f32_16x16x32_bf16 v[38:41], v[166:169], v[190:193], v[38:41]
	v_mfma_f32_16x16x32_bf16 v[34:37], v[174:177], v[190:193], v[34:37]
	v_mfma_f32_16x16x32_bf16 v[22:25], v[166:169], v[198:201], v[22:25]
	v_mfma_f32_16x16x32_bf16 v[18:21], v[174:177], v[198:201], v[18:21]
	v_mfma_f32_16x16x32_bf16 v[6:9], v[166:169], v[206:209], v[6:9]
	v_mfma_f32_16x16x32_bf16 v[2:5], v[174:177], v[206:209], v[2:5]
	s_barrier
	s_add_i32 s66, 0, 0x18000
	s_add_i32 s67, 0, 0x1c000
	v_add_u32_e32 v158, s66, v141
	v_add_u32_e32 v174, s67, v141
	ds_read_b128 v[146:149], v158
	ds_read_b128 v[150:153], v158 offset:1024
	ds_read_b128 v[154:157], v158 offset:2048
	ds_read_b128 v[158:161], v158 offset:3072
	ds_read_b128 v[162:165], v174
	ds_read_b128 v[166:169], v174 offset:1024
	ds_read_b128 v[170:173], v174 offset:2048
	ds_read_b128 v[174:177], v174 offset:3072
	s_add_u32 s40, s40, 0x40000
	s_addc_u32 s41, s41, 0
	s_mov_b32 m0, s51
	v_lshl_add_u64 v[216:217], s[40:41], 0, v[130:131]
	ds_read_b128 v[178:181], v144 offset:32768
	ds_read_b128 v[182:185], v144 offset:33792
	ds_read_b128 v[186:189], v144 offset:34816
	ds_read_b128 v[190:193], v144 offset:35840
	ds_read_b128 v[194:197], v144 offset:36864
	ds_read_b128 v[198:201], v144 offset:37888
	ds_read_b128 v[202:205], v144 offset:38912
	ds_read_b128 v[206:209], v144 offset:39936
	global_load_lds_dwordx4 v[216:217], off
	v_lshl_add_u64 v[216:217], s[40:41], 0, v[132:133]
	s_mov_b32 m0, s52
	s_nop 0
	global_load_lds_dwordx4 v[216:217], off
	s_waitcnt vmcnt(8)
	s_waitcnt lgkmcnt(0)
	s_barrier
	s_waitcnt lgkmcnt(0)
	v_mfma_f32_16x16x32_bf16 v[126:129], v[146:149], v[178:181], v[126:129]
	v_mfma_f32_16x16x32_bf16 v[122:125], v[154:157], v[178:181], v[122:125]
	v_mfma_f32_16x16x32_bf16 v[110:113], v[146:149], v[186:189], v[110:113]
	v_mfma_f32_16x16x32_bf16 v[106:109], v[154:157], v[186:189], v[106:109]
	v_mfma_f32_16x16x32_bf16 v[94:97], v[146:149], v[194:197], v[94:97]
	v_mfma_f32_16x16x32_bf16 v[90:93], v[154:157], v[194:197], v[90:93]
	v_mfma_f32_16x16x32_bf16 v[78:81], v[146:149], v[202:205], v[78:81]
	v_mfma_f32_16x16x32_bf16 v[74:77], v[154:157], v[202:205], v[74:77]
	v_mfma_f32_16x16x32_bf16 v[126:129], v[150:153], v[182:185], v[126:129]
	v_mfma_f32_16x16x32_bf16 v[122:125], v[158:161], v[182:185], v[122:125]
	v_mfma_f32_16x16x32_bf16 v[110:113], v[150:153], v[190:193], v[110:113]
	v_mfma_f32_16x16x32_bf16 v[106:109], v[158:161], v[190:193], v[106:109]
	v_mfma_f32_16x16x32_bf16 v[94:97], v[150:153], v[198:201], v[94:97]
	v_mfma_f32_16x16x32_bf16 v[90:93], v[158:161], v[198:201], v[90:93]
	v_mfma_f32_16x16x32_bf16 v[78:81], v[150:153], v[206:209], v[78:81]
	v_mfma_f32_16x16x32_bf16 v[74:77], v[158:161], v[206:209], v[74:77]
	v_mfma_f32_16x16x32_bf16 v[118:121], v[162:165], v[178:181], v[118:121]
	v_mfma_f32_16x16x32_bf16 v[114:117], v[170:173], v[178:181], v[114:117]
	v_mfma_f32_16x16x32_bf16 v[102:105], v[162:165], v[186:189], v[102:105]
	v_mfma_f32_16x16x32_bf16 v[98:101], v[170:173], v[186:189], v[98:101]
	v_mfma_f32_16x16x32_bf16 v[86:89], v[162:165], v[194:197], v[86:89]
	v_mfma_f32_16x16x32_bf16 v[82:85], v[170:173], v[194:197], v[82:85]
	v_mfma_f32_16x16x32_bf16 v[70:73], v[162:165], v[202:205], v[70:73]
	v_mfma_f32_16x16x32_bf16 v[66:69], v[170:173], v[202:205], v[66:69]
	v_mfma_f32_16x16x32_bf16 v[118:121], v[166:169], v[182:185], v[118:121]
	v_mfma_f32_16x16x32_bf16 v[114:117], v[174:177], v[182:185], v[114:117]
	v_mfma_f32_16x16x32_bf16 v[102:105], v[166:169], v[190:193], v[102:105]
	v_mfma_f32_16x16x32_bf16 v[98:101], v[174:177], v[190:193], v[98:101]
	v_mfma_f32_16x16x32_bf16 v[86:89], v[166:169], v[198:201], v[86:89]
	v_mfma_f32_16x16x32_bf16 v[82:85], v[174:177], v[198:201], v[82:85]
	v_mfma_f32_16x16x32_bf16 v[70:73], v[166:169], v[206:209], v[70:73]
	v_mfma_f32_16x16x32_bf16 v[66:69], v[174:177], v[206:209], v[66:69]
	s_barrier
; #define PG8_STAGE(bufoff, gbase, voff) do { _Pragma("unroll") for (int _i = 0; _i < 2; ++_i) \
;         __builtin_amdgcn_global_load_lds((const unsigned*)((const char*)(gbase) + (voff)[_i]), (PG8_LAS unsigned*)(lds + (bufoff) + ldsw + _i * 8192), 16, 0, 0); } while (0)
; #define PG8_LDA(dst, b, h) do { _Pragma("unroll") for (int m = 0; m < 4; ++m) _Pragma("unroll") for (int k = 0; k < 2; ++k) dst[m][k] = *(const PG8_LAS bf16x8*)(lds + PG8_SA(b, h) + aoff + m * 2048 + k * 1024); } while (0)
; #define PG8_MMA(ai, bj, At, Bt) do { __builtin_amdgcn_s_setprio(1); _Pragma("unroll") for (int m = 0; m < 4; ++m) _Pragma("unroll") for (int n = 0; n < 2; ++n) _Pragma("unroll") for (int k = 0; k < 2; ++k) \
;         acc[ai][bj][m][n] = __builtin_amdgcn_mfma_f32_16x16x32_bf16(Bt[n][k], At[m][k], acc[ai][bj][m][n], 0, 0, 0); __builtin_amdgcn_s_setprio(0); } while (0)
; #define PG8_WAIT_V(n) asm volatile("s_waitcnt vmcnt(" #n ")" ::: "memory")
; #define PG8_WAIT_L(n) asm volatile("s_waitcnt lgkmcnt(" #n ")" ::: "memory")
; #define PG8_BAR __builtin_amdgcn_s_barrier()
; #define PG8_SCHED __builtin_amdgcn_sched_barrier(0)
; template <class Epi, class Sched, bool ALIGN_EPI = false, bool SP2 = false>
; __device__ __forceinline__ void gemm_phase(PG8_LAS unsigned char* lds, const Gemm g, const Sched& S, const Epi& E) {
;     ...
;         for (int t = 0; t < nt; t += 2) {
;             const bool last = (t == nt - 2);
;             const char* a1 = cA + (size_t)(t + 1) * kstep;
;             const char* a2 = last ? nA : cA + (size_t)(t + 2) * kstep; const char* b2 = last ? nB : cB + (size_t)(t + 2) * kstep;
;     ...
;             PG8_LDA(At, 1, 1); PG8_STAGE(PG8_SB(1, 0), b3, voffB); PG8_STAGE(PG8_SB(1, 1), b3 + hstep, voffB); PG8_STAGE(PG8_SA(1, 0), a3, voffA);
;             PG8_WAIT_V(8); PG8_WAIT_L(0); PG8_BAR; PG8_MMA(1, 0, At, B0); PG8_MMA(1, 1, At, B1); PG8_BAR; PG8_SCHED;
	s_add_i32 s40, s66, s48
	v_lshl_add_u64 v[138:139], v[138:139], 0, s[30:31]
	s_mov_b32 m0, s40
	ds_read_b128 v[178:181], v144 offset:49152
	ds_read_b128 v[182:185], v144 offset:50176
	ds_read_b128 v[186:189], v144 offset:51200
	ds_read_b128 v[190:193], v144 offset:52224
	ds_read_b128 v[194:197], v144 offset:53248
	ds_read_b128 v[198:201], v144 offset:54272
	ds_read_b128 v[202:205], v144 offset:55296
	ds_read_b128 v[206:209], v144 offset:56320
	global_load_lds_dwordx4 v[138:139], off
	s_add_i32 m0, s40, 0x2000
	s_add_u32 s38, s38, 0x40080
	v_lshl_add_u64 v[138:139], v[210:211], 0, s[30:31]
	s_addc_u32 s39, s39, 0
	s_add_i32 s40, s67, s48
	global_load_lds_dwordx4 v[138:139], off
	v_lshl_add_u64 v[138:139], s[38:39], 0, v[130:131]
	s_mov_b32 m0, s40
	s_nop 0
	global_load_lds_dwordx4 v[138:139], off
	v_lshl_add_u64 v[138:139], s[38:39], 0, v[132:133]
	s_add_i32 m0, s40, 0x2000
	s_nop 0
	global_load_lds_dwordx4 v[138:139], off
	v_lshl_add_u64 v[138:139], v[212:213], 0, s[30:31]
	s_mov_b32 m0, s53
	s_nop 0
	global_load_lds_dwordx4 v[138:139], off
	v_lshl_add_u64 v[138:139], v[214:215], 0, s[30:31]
	s_mov_b32 m0, s54
	s_nop 0
	global_load_lds_dwordx4 v[138:139], off
	s_waitcnt vmcnt(8)
	s_waitcnt lgkmcnt(0)
	s_barrier
	s_waitcnt lgkmcnt(0)
	v_mfma_f32_16x16x32_bf16 v[62:65], v[146:149], v[178:181], v[62:65]
	v_mfma_f32_16x16x32_bf16 v[58:61], v[154:157], v[178:181], v[58:61]
	v_mfma_f32_16x16x32_bf16 v[46:49], v[146:149], v[186:189], v[46:49]
	v_mfma_f32_16x16x32_bf16 v[42:45], v[154:157], v[186:189], v[42:45]
	v_mfma_f32_16x16x32_bf16 v[30:33], v[146:149], v[194:197], v[30:33]
	v_mfma_f32_16x16x32_bf16 v[26:29], v[154:157], v[194:197], v[26:29]
	v_mfma_f32_16x16x32_bf16 v[14:17], v[146:149], v[202:205], v[14:17]
	v_mfma_f32_16x16x32_bf16 v[10:13], v[154:157], v[202:205], v[10:13]
	v_mfma_f32_16x16x32_bf16 v[62:65], v[150:153], v[182:185], v[62:65]
	v_mfma_f32_16x16x32_bf16 v[58:61], v[158:161], v[182:185], v[58:61]
	v_mfma_f32_16x16x32_bf16 v[46:49], v[150:153], v[190:193], v[46:49]
	v_mfma_f32_16x16x32_bf16 v[42:45], v[158:161], v[190:193], v[42:45]
	v_mfma_f32_16x16x32_bf16 v[30:33], v[150:153], v[198:201], v[30:33]
	v_mfma_f32_16x16x32_bf16 v[26:29], v[158:161], v[198:201], v[26:29]
	v_mfma_f32_16x16x32_bf16 v[14:17], v[150:153], v[206:209], v[14:17]
	v_mfma_f32_16x16x32_bf16 v[10:13], v[158:161], v[206:209], v[10:13]
	v_mfma_f32_16x16x32_bf16 v[54:57], v[162:165], v[178:181], v[54:57]
	v_mfma_f32_16x16x32_bf16 v[50:53], v[170:173], v[178:181], v[50:53]
	v_mfma_f32_16x16x32_bf16 v[38:41], v[162:165], v[186:189], v[38:41]
	v_mfma_f32_16x16x32_bf16 v[34:37], v[170:173], v[186:189], v[34:37]
	v_mfma_f32_16x16x32_bf16 v[22:25], v[162:165], v[194:197], v[22:25]
	v_mfma_f32_16x16x32_bf16 v[18:21], v[170:173], v[194:197], v[18:21]
	v_mfma_f32_16x16x32_bf16 v[6:9], v[162:165], v[202:205], v[6:9]
	v_mfma_f32_16x16x32_bf16 v[2:5], v[170:173], v[202:205], v[2:5]
	v_mfma_f32_16x16x32_bf16 v[54:57], v[166:169], v[182:185], v[54:57]
	v_mfma_f32_16x16x32_bf16 v[50:53], v[174:177], v[182:185], v[50:53]
	v_mfma_f32_16x16x32_bf16 v[38:41], v[166:169], v[190:193], v[38:41]
	v_mfma_f32_16x16x32_bf16 v[34:37], v[174:177], v[190:193], v[34:37]
	v_mfma_f32_16x16x32_bf16 v[22:25], v[166:169], v[198:201], v[22:25]
	v_mfma_f32_16x16x32_bf16 v[18:21], v[174:177], v[198:201], v[18:21]
	v_mfma_f32_16x16x32_bf16 v[6:9], v[166:169], v[206:209], v[6:9]
	v_mfma_f32_16x16x32_bf16 v[2:5], v[174:177], v[206:209], v[2:5]
	s_barrier
	s_add_i32 s65, s65, 2
	s_add_u32 s36, s36, 0x100
	s_addc_u32 s37, s37, 0
	s_add_u32 s63, s63, 0x100
	s_addc_u32 s64, s64, 0
	s_cmp_gt_u32 s65, 13
	s_cbranch_scc0 .LBB0_1309
	s_and_b64 vcc, exec, s[34:35]
	s_cbranch_vccz .LBB0_1312
	s_barrier
